# intra-chunk phase (prompt half): old-y tiles loaded with coalesced dwordx4 and redistributed through LDS
# baseline (speedup 1.0000x reference)
; #define MFMA32(a, b, c) __builtin_amdgcn_mfma_f32_32x32x16_bf16((a), (b), (c), 0, 0, 0)
; DI float log2_gamma(float x) { return -__builtin_amdgcn_logf(1.0f + __builtin_amdgcn_exp2f(-1.4426950408889634f * x)); }
; template <bool DRY, bool H1>
; DI void intra_phase(LAS unsigned char* lds, const Params& p) {
;     ...
;   for (int item = blockIdx.x; item < 512; item += gridDim.x) {
;     const int hd = item & 3, tb = (item >> 2) * 128;
;     const float lgf = log2_gamma(p.dec_f[hd]), lgb = log2_gamma(p.dec_b[hd]);
;     const int icol = 32 * ib + r;
;     {
;       bf16x8 qf[16];
;       const unsigned qo = (unsigned)(item) * 65536u + (unsigned)ib * 16384u + (unsigned)lane * 16u;
; #pragma unroll
;       for (int s = 0; s < 16; ++s) qf[s] = ldg16(qr, qo + 1024u * s);
; #pragma unroll
;       for (int jj = 0; jj < 2; ++jj) {
;         const int jt = 2 * wh + jj;
;         f32x16 pt;
; #pragma unroll
;         for (int i = 0; i < 16; ++i) pt[i] = 0.f;
;         const unsigned ko = (unsigned)(item) * 65536u + (unsigned)jt * 16384u + (unsigned)lane * 16u;
; #pragma unroll
;         for (int s = 0; s < 16; ++s) pt = MFMA32(ldg16(kr, ko + 1024u * s), qf[s], pt);
.LBB0_58:
	s_lshl_b32 s78, s2, 16
	v_or_b32_e32 v8, s78, v93
	v_add_u32_e32 v90, v8, v97
	global_load_dwordx4 v[0:3], v90, s[0:1]
	v_or_b32_e32 v91, s78, v94
	global_load_dwordx4 v[4:7], v91, s[92:93]
	v_or_b32_e32 v12, 0x400, v90
	global_load_dwordx4 v[32:35], v12, s[0:1]
	v_add_u32_e32 v167, v8, v130
	global_load_dwordx4 v[8:11], v167, s[0:1]
	v_or_b32_e32 v168, 0x1400, v167
	v_or_b32_e32 v172, 0x1800, v90
	v_or_b32_e32 v176, 0x1800, v167
	s_and_b32 s94, s2, 3
	s_lshl_b32 s78, s94, 2
	s_mov_b64 s[66:67], s[18:19]
	s_mov_b64 s[64:65], s[16:17]
	v_or_b32_e32 v178, 0x2000, v167
	v_or_b32_e32 v182, 0x2c00, v91
	v_or_b32_e32 v186, 0x3400, v91
	v_or_b32_e32 v195, 0x3400, v167
	s_mov_b64 s[60:61], s[12:13]
	v_readlane_b32 s60, v255, 49
	v_readlane_b32 s61, v255, 50
	s_mov_b64 s[62:63], s[14:15]
	s_waitcnt vmcnt(2)
	v_mfma_f32_32x32x16_bf16 v[16:31], v[0:3], v[4:7], 0
	v_or_b32_e32 v0, 0x1400, v91
	global_load_dwordx4 v[86:89], v0, s[92:93]
	v_or_b32_e32 v12, 0x400, v91
	global_load_dwordx4 v[36:39], v12, s[92:93]
	v_or_b32_e32 v12, 0x400, v167
	global_load_dwordx4 v[40:43], v12, s[0:1]
	v_or_b32_e32 v12, 0x800, v90
	global_load_dwordx4 v[44:47], v12, s[0:1]
	s_waitcnt vmcnt(2)
	v_mfma_f32_32x32x16_bf16 v[16:31], v[32:35], v[36:39], v[16:31]
	global_load_dwordx4 v[168:171], v168, s[0:1]
	v_or_b32_e32 v12, 0x800, v91
	global_load_dwordx4 v[48:51], v12, s[92:93]
	v_or_b32_e32 v12, 0x800, v167
	global_load_dwordx4 v[52:55], v12, s[0:1]
	global_load_dwordx4 v[32:35], v172, s[0:1]
	v_or_b32_e32 v172, 0x1800, v91
	s_waitcnt vmcnt(2)
	v_mfma_f32_32x32x16_bf16 v[16:31], v[44:47], v[48:51], v[16:31]
	v_or_b32_e32 v44, 0x1c00, v91
	global_load_dwordx4 v[44:47], v44, s[92:93]
	v_or_b32_e32 v12, 0xc00, v90
	global_load_dwordx4 v[56:59], v12, s[0:1]
	v_or_b32_e32 v12, 0xc00, v91
	global_load_dwordx4 v[60:63], v12, s[92:93]
	v_or_b32_e32 v12, 0xc00, v167
	global_load_dwordx4 v[64:67], v12, s[0:1]
	s_waitcnt vmcnt(1)
	v_mfma_f32_32x32x16_bf16 v[16:31], v[56:59], v[60:63], v[16:31]
	v_or_b32_e32 v56, 0x2000, v91
	global_load_dwordx4 v[56:59], v56, s[92:93]
	v_or_b32_e32 v12, 0x1000, v90
	global_load_dwordx4 v[68:71], v12, s[0:1]
	s_nop 0
	global_load_dwordx4 v[172:175], v172, s[92:93]
	v_or_b32_e32 v12, 0x1000, v91
	global_load_dwordx4 v[72:75], v12, s[92:93]
	v_or_b32_e32 v12, 0x1000, v167
	global_load_dwordx4 v[78:81], v12, s[0:1]
	v_or_b32_e32 v12, 0x1400, v90
	global_load_dwordx4 v[82:85], v12, s[0:1]
	v_mfma_f32_32x32x16_bf16 v[0:15], v[8:11], v[4:7], 0
	v_mfma_f32_32x32x16_bf16 v[0:15], v[40:43], v[36:39], v[0:15]
	global_load_dwordx4 v[36:39], v176, s[0:1]
	v_or_b32_e32 v40, 0x1c00, v90
	global_load_dwordx4 v[40:43], v40, s[0:1]
	v_or_b32_e32 v176, 0x1c00, v167
	v_mfma_f32_32x32x16_bf16 v[0:15], v[52:55], v[48:51], v[0:15]
	global_load_dwordx4 v[48:51], v176, s[0:1]
	v_or_b32_e32 v52, 0x2000, v90
	global_load_dwordx4 v[52:55], v52, s[0:1]
	v_mov_b32_e32 v176, s78
	global_load_dword v194, v176, s[64:65]
	s_nop 0
	global_load_dword v176, v176, s[66:67]
	s_lshl_b32 s78, s2, 5
	s_and_b32 s78, s78, 0xffffff80
	s_waitcnt vmcnt(12)
	v_mfma_f32_32x32x16_bf16 v[0:15], v[64:67], v[60:63], v[0:15]
	global_load_dwordx4 v[60:63], v178, s[0:1]
	v_or_b32_e32 v64, 0x2400, v90
	global_load_dwordx4 v[64:67], v64, s[0:1]
	s_waitcnt vmcnt(10)
	v_mfma_f32_32x32x16_bf16 v[16:31], v[68:71], v[72:75], v[16:31]
	v_or_b32_e32 v68, 0x2400, v91
	global_load_dwordx4 v[68:71], v68, s[92:93]
	s_waitcnt vmcnt(10)
	v_mfma_f32_32x32x16_bf16 v[0:15], v[78:81], v[72:75], v[0:15]
	v_or_b32_e32 v78, 0x2800, v90
	global_load_dwordx4 v[78:81], v78, s[0:1]
	s_waitcnt vmcnt(10)
	v_mfma_f32_32x32x16_bf16 v[16:31], v[82:85], v[86:89], v[16:31]
	v_mfma_f32_32x32x16_bf16 v[0:15], v[168:171], v[86:89], v[0:15]
	global_load_dwordx4 v[86:89], v182, s[92:93]
	v_or_b32_e32 v182, 0x3000, v91
	v_or_b32_e32 v168, 0x3000, v90
	global_load_dwordx4 v[168:171], v168, s[0:1]
	v_mfma_f32_32x32x16_bf16 v[16:31], v[32:35], v[172:175], v[16:31]
	global_load_dwordx4 v[32:35], v182, s[92:93]
	v_or_b32_e32 v182, 0x3400, v90
	global_load_dwordx4 v[182:185], v182, s[0:1]
	v_or_b32_e32 v178, 0x2400, v167
	global_load_dwordx4 v[72:75], v178, s[0:1]
	s_waitcnt vmcnt(14)
	v_mfma_f32_32x32x16_bf16 v[0:15], v[36:39], v[172:175], v[0:15]
	global_load_dwordx4 v[36:39], v186, s[92:93]
	v_or_b32_e32 v178, 0x2800, v91
	global_load_dwordx4 v[82:85], v178, s[92:93]
	v_or_b32_e32 v186, 0x3800, v91
	v_or_b32_e32 v172, 0x3800, v90
	global_load_dwordx4 v[172:175], v172, s[0:1]
	s_waitcnt vmcnt(16)
	v_mfma_f32_32x32x16_bf16 v[16:31], v[40:43], v[44:47], v[16:31]
	global_load_dwordx4 v[40:43], v186, s[92:93]
	v_or_b32_e32 v178, 0x2c00, v90
	global_load_dwordx4 v[178:181], v178, s[0:1]
	v_or_b32_e32 v90, 0x3c00, v90
	global_load_dwordx4 v[186:189], v90, s[0:1]
	v_or_b32_e32 v90, 0x3c00, v91
	global_load_dwordx4 v[190:193], v90, s[92:93]
	v_or_b32_e32 v90, 0x2800, v167
	s_waitcnt vmcnt(19)
	v_mfma_f32_32x32x16_bf16 v[0:15], v[48:51], v[44:47], v[0:15]
	global_load_dwordx4 v[44:47], v90, s[0:1]
	v_or_b32_e32 v48, 0x2c00, v167
	global_load_dwordx4 v[48:51], v48, s[0:1]
	v_or_b32_e32 v91, 0x3000, v167
	v_or_b32_e32 v90, 0x3800, v167
	v_or_b32_e32 v167, 0x3c00, v167
	s_waitcnt vmcnt(20)
	v_mfma_f32_32x32x16_bf16 v[16:31], v[52:55], v[56:59], v[16:31]
	s_waitcnt vmcnt(19)
	v_mul_f32_e32 v52, 0xbfb8aa3b, v194
	s_waitcnt vmcnt(18)
	v_mul_f32_e32 v53, 0xbfb8aa3b, v176
	v_exp_f32_e32 v176, v52
	v_exp_f32_e32 v198, v53
	global_load_dwordx4 v[52:55], v91, s[0:1]
	s_nop 0
	global_load_dwordx4 v[194:197], v195, s[0:1]
	v_add_f32_e32 v91, 1.0, v176
	s_waitcnt vmcnt(19)
; #define LAS __attribute__((address_space(3)))
; #define MFMA32(a, b, c) __builtin_amdgcn_mfma_f32_32x32x16_bf16((a), (b), (c), 0, 0, 0)
; #define EX2(x) __builtin_amdgcn_exp2f(x)
; template <bool DRY, bool H1>
; DI void intra_phase(LAS unsigned char* lds, const Params& p) {
;     ...
;         f32x16 pt;
; #pragma unroll
;         for (int i = 0; i < 16; ++i) pt[i] = 0.f;
;         const unsigned ko = (unsigned)(item) * 65536u + (unsigned)jt * 16384u + (unsigned)lane * 16u;
; #pragma unroll
;         for (int s = 0; s < 16; ++s) pt = MFMA32(ldg16(kr, ko + 1024u * s), qf[s], pt);
; #pragma unroll
;         for (int gq = 0; gq < 4; ++gq) {
;           float f[4];
; #pragma unroll
;           for (int e = 0; e < 4; ++e) {
;             const int df = icol - (32 * jt + 8 * gq + 4 * h + e);
;             f[e] = pt[4 * gq + e] * EX2(df >= 0 ? lgf * (float)df : lgb * (float)(-df));
;           }
;           u32x2 a; a.x = rne_pk(f[0], f[1]); a.y = rne_pk(f[2], f[3]);
;           *(LAS u32x2*)(Pimg + icol * 272 + (32 * jt + 8 * gq + 4 * h) * 2) = a;
;         }
	v_mfma_f32_32x32x16_bf16 v[0:15], v[60:63], v[56:59], v[0:15]
	v_add_f32_e32 v56, 1.0, v198
	v_log_f32_e32 v176, v56
	global_load_dwordx4 v[56:59], v90, s[0:1]
	global_load_dwordx4 v[60:63], v167, s[0:1]
	v_log_f32_e32 v91, v91
	v_mul_f32_e64 v167, v98, -v176
	v_mul_f32_e64 v199, v104, -v176
	s_waitcnt vmcnt(19)
	v_mfma_f32_32x32x16_bf16 v[16:31], v[64:67], v[68:71], v[16:31]
	v_mul_f32_e64 v90, v99, -v91
	v_cndmask_b32_e64 v90, v90, v167, s[60:61]
	v_readlane_b32 s60, v255, 51
	v_mul_f32_e64 v64, v101, -v91
	v_mul_f32_e64 v65, v100, -v176
	v_readlane_b32 s61, v255, 52
	v_mul_f32_e64 v66, v103, -v91
	s_waitcnt vmcnt(11)
	v_mfma_f32_32x32x16_bf16 v[16:31], v[78:81], v[82:85], v[16:31]
	v_cndmask_b32_e64 v65, v64, v65, s[60:61]
	v_readlane_b32 s60, v255, 53
	v_mul_f32_e64 v67, v102, -v176
	v_readlane_b32 s61, v255, 54
	v_mul_f32_e64 v198, v105, -v91
	v_mul_f32_e64 v200, v107, -v91
	v_cndmask_b32_e64 v66, v66, v67, s[60:61]
	s_waitcnt vmcnt(8)
	v_mfma_f32_32x32x16_bf16 v[16:31], v[178:181], v[86:89], v[16:31]
	v_readlane_b32 s60, v255, 55
	v_readlane_b32 s61, v255, 56
	v_cndmask_b32_e64 v67, v198, v199, s[74:75]
	v_exp_f32_e32 v64, v90
	v_exp_f32_e32 v65, v65
	v_exp_f32_e32 v66, v66
	v_exp_f32_e32 v67, v67
	v_mfma_f32_32x32x16_bf16 v[0:15], v[72:75], v[68:71], v[0:15]
	v_mul_f32_e64 v69, v109, -v91
	v_mul_f32_e64 v70, v108, -v176
	v_cndmask_b32_e64 v69, v69, v70, s[60:61]
	v_readlane_b32 s60, v255, 57
	v_mul_f32_e64 v68, v106, -v176
	v_mul_f32_e64 v71, v111, -v91
	v_mul_f32_e64 v72, v110, -v176
	v_mfma_f32_32x32x16_bf16 v[16:31], v[168:171], v[32:35], v[16:31]
	v_mul_f32_e64 v73, v113, -v91
	v_mul_f32_e64 v74, v112, -v176
	v_readlane_b32 s61, v255, 58
	v_cndmask_b32_e64 v68, v200, v68, s[10:11]
	v_exp_f32_e32 v68, v68
	v_cndmask_b32_e64 v70, v71, v72, s[60:61]
	v_cndmask_b32_e64 v71, v73, v74, s[20:21]
	s_waitcnt vmcnt(5)
	v_mfma_f32_32x32x16_bf16 v[0:15], v[44:47], v[82:85], v[0:15]
	v_exp_f32_e32 v69, v69
	v_exp_f32_e32 v70, v70
	v_exp_f32_e32 v71, v71
	v_mul_f32_e64 v75, v115, -v91
	v_mul_f32_e64 v78, v114, -v176
	v_mul_f32_e64 v79, v117, -v91
	v_mul_f32_e64 v80, v116, -v176
	v_mfma_f32_32x32x16_bf16 v[16:31], v[182:185], v[36:39], v[16:31]
	v_mul_f32_e64 v81, v119, -v91
	v_mul_f32_e64 v201, v118, -v176
	v_mul_f32_e64 v203, v121, -v91
	v_mul_f32_e64 v178, v120, -v176
	v_mul_f32_e64 v179, v123, -v91
	v_mul_f32_e64 v180, v122, -v176
	v_mul_f32_e64 v181, v125, -v91
	s_waitcnt vmcnt(4)
	v_mfma_f32_32x32x16_bf16 v[0:15], v[48:51], v[86:89], v[0:15]
	v_mul_f32_e64 v204, v124, -v176
	v_mul_f32_e64 v205, v127, -v91
	v_mul_f32_e64 v206, v126, -v176
	v_cndmask_b32_e64 v72, v75, v78, s[22:23]
	v_cndmask_b32_e64 v73, v79, v80, s[24:25]
	v_cndmask_b32_e64 v74, v81, v201, s[26:27]
	v_cndmask_b32_e64 v75, v203, v178, s[28:29]
	v_mfma_f32_32x32x16_bf16 v[16:31], v[172:175], v[40:43], v[16:31]
	v_cndmask_b32_e64 v78, v179, v180, s[30:31]
	v_cndmask_b32_e64 v79, v181, v204, s[34:35]
	v_exp_f32_e32 v72, v72
	v_exp_f32_e32 v73, v73
	v_exp_f32_e32 v74, v74
	v_exp_f32_e32 v75, v75
	v_exp_f32_e32 v78, v78
	s_waitcnt vmcnt(3)
	v_mfma_f32_32x32x16_bf16 v[0:15], v[52:55], v[32:35], v[0:15]
	v_exp_f32_e32 v79, v79
	v_mfma_f32_32x32x16_bf16 v[16:31], v[186:189], v[190:193], v[16:31]
	s_waitcnt vmcnt(2)
	v_mfma_f32_32x32x16_bf16 v[0:15], v[194:197], v[36:39], v[0:15]
	s_nop 9
	v_mul_f32_e64 v16, v64, v16
	v_mul_f32_e64 v17, v65, v17
	v_mul_f32_e64 v18, v66, v18
	v_mul_f32_e64 v19, v67, v19
	v_mul_f32_e64 v20, v68, v20
	v_mul_f32_e64 v21, v69, v21
	v_pk_mul_f32 v[22:23], v[70:71], v[22:23]
	v_cvt_pk_bf16_f32 v16, v16, v17
	v_cvt_pk_bf16_f32 v17, v18, v19
	v_cvt_pk_bf16_f32 v18, v20, v21
	v_cvt_pk_bf16_f32 v19, v22, v23
	s_waitcnt vmcnt(1)
	v_mfma_f32_32x32x16_bf16 v[0:15], v[56:59], v[40:43], v[0:15]
	ds_write2_b64 v164, v[16:17], v[18:19] offset1:2
	v_mul_f32_e64 v17, v129, -v91
	v_mul_f32_e64 v18, v128, -v176
	v_cndmask_b32_e64 v16, v205, v206, s[36:37]
	v_cndmask_b32_e64 v17, v17, v18, s[38:39]
	v_exp_f32_e32 v16, v16
	v_exp_f32_e32 v17, v17
	v_pk_mul_f32 v[24:25], v[72:73], v[24:25]
	v_pk_mul_f32 v[26:27], v[74:75], v[26:27]
	v_pk_mul_f32 v[18:19], v[78:79], v[28:29]
	v_pk_mul_f32 v[16:17], v[16:17], v[30:31]
	v_cvt_pk_bf16_f32 v20, v24, v25
	v_cvt_pk_bf16_f32 v21, v26, v27
	v_cvt_pk_bf16_f32 v18, v18, v19
	v_cvt_pk_bf16_f32 v19, v16, v17
	v_mul_f32_e64 v16, v132, -v91
	v_mul_f32_e64 v17, v131, -v176
	s_waitcnt vmcnt(0)
; #define LAS __attribute__((address_space(3)))
; #define EX2(x) __builtin_amdgcn_exp2f(x)
; template <bool DRY, bool H1>
; DI void intra_phase(LAS unsigned char* lds, const Params& p) {
;     ...
;         for (int gq = 0; gq < 4; ++gq) {
;           float f[4];
; #pragma unroll
;           for (int e = 0; e < 4; ++e) {
;             const int df = icol - (32 * jt + 8 * gq + 4 * h + e);
;             f[e] = pt[4 * gq + e] * EX2(df >= 0 ? lgf * (float)df : lgb * (float)(-df));
;           }
;           u32x2 a; a.x = rne_pk(f[0], f[1]); a.y = rne_pk(f[2], f[3]);
;           *(LAS u32x2*)(Pimg + icol * 272 + (32 * jt + 8 * gq + 4 * h) * 2) = a;
;         }
;       }
;     }
;     __syncthreads();
;     {
;       bf16x8 pf[8];
; #pragma unroll
;       for (int s = 0; s < 8; ++s) pf[s] = *(const LAS bf16x8*)(Pimg + icol * 272 + (16 * s + 8 * h) * 2);
;       float sq2 = 0.f;
;       const unsigned vo = (unsigned)(item) * 131072u + (unsigned)(8 * wh) * 8192u + (unsigned)lane * 16u;
;       const unsigned yo = (unsigned)((tb + icol) * 2048 + hd * 512 + 256 * wh + 4 * h) * 2u;
;       bf16x8 va[2][8]; u32x2 yold[2][4], yol2[2][4];
; #pragma unroll
;       for (int gq = 0; gq < 4; ++gq) { yol2[0][gq] = (u32x2){0u, 0u}; yol2[1][gq] = (u32x2){0u, 0u}; }
; #pragma unroll
;       for (int s = 0; s < 8; ++s) va[0][s] = ldg16(vT, vo + 1024u * s);
; #pragma unroll
;       for (int gq = 0; gq < 4; ++gq) { yold[0][gq] = *(const u32x2*)((const char*)y + (yo + 16u * gq)); if constexpr (H1) yol2[0][gq] = *(const u32x2*)((const char*)yb + (yo + 16u * gq)); }
; #pragma unroll
;       for (int t = 0; t < 8; ++t) {
;         if (t < 7) {
; #pragma unroll
;           for (int s = 0; s < 8; ++s) va[(t + 1) & 1][s] = ldg16(vT, vo + (unsigned)(t + 1) * 8192u + 1024u * s);
; #pragma unroll
;           for (int gq = 0; gq < 4; ++gq) { yold[(t + 1) & 1][gq] = *(const u32x2*)((const char*)y + (yo + 64u * (t + 1) + 16u * gq)); if constexpr (H1) yol2[(t + 1) & 1][gq] = *(const u32x2*)((const char*)yb + (yo + 64u * (t + 1) + 16u * gq)); }
	v_mfma_f32_32x32x16_bf16 v[0:15], v[60:63], v[190:193], v[0:15]
	ds_write2_b64 v164, v[20:21], v[18:19] offset0:4 offset1:6
	v_cndmask_b32_e64 v16, v16, v17, s[40:41]
	v_mul_f32_e64 v17, v134, -v91
	v_mul_f32_e64 v18, v133, -v176
	v_cndmask_b32_e64 v17, v17, v18, s[42:43]
	v_mul_f32_e64 v18, v136, -v91
	v_mul_f32_e64 v19, v135, -v176
	v_cndmask_b32_e64 v18, v18, v19, s[44:45]
	v_mul_f32_e64 v19, v138, -v91
	v_mul_f32_e64 v20, v137, -v176
	v_exp_f32_e32 v16, v16
	v_exp_f32_e32 v17, v17
	v_cndmask_b32_e64 v19, v19, v20, s[46:47]
	v_exp_f32_e32 v18, v18
	v_exp_f32_e32 v19, v19
	v_pk_mul_f32 v[0:1], v[16:17], v[0:1]
	v_mul_f32_e64 v16, v140, -v91
	v_mul_f32_e64 v17, v139, -v176
	v_pk_mul_f32 v[2:3], v[18:19], v[2:3]
	v_cndmask_b32_e64 v16, v16, v17, s[48:49]
	v_mul_f32_e64 v17, v142, -v91
	v_mul_f32_e64 v18, v141, -v176
	v_cndmask_b32_e64 v17, v17, v18, s[50:51]
	v_mul_f32_e64 v18, v144, -v91
	v_mul_f32_e64 v19, v143, -v176
	v_cndmask_b32_e64 v18, v18, v19, s[52:53]
	v_mul_f32_e64 v19, v146, -v91
	v_mul_f32_e64 v20, v145, -v176
	v_exp_f32_e32 v16, v16
	v_exp_f32_e32 v17, v17
	v_cndmask_b32_e64 v19, v19, v20, s[54:55]
	v_exp_f32_e32 v18, v18
	v_exp_f32_e32 v19, v19
	v_cvt_pk_bf16_f32 v0, v0, v1
	v_cvt_pk_bf16_f32 v1, v2, v3
	v_pk_mul_f32 v[2:3], v[16:17], v[4:5]
	v_pk_mul_f32 v[4:5], v[18:19], v[6:7]
	v_cvt_pk_bf16_f32 v2, v2, v3
	v_mul_f32_e64 v3, v148, -v91
	v_mul_f32_e64 v6, v147, -v176
	v_cndmask_b32_e64 v3, v3, v6, s[56:57]
	v_exp_f32_e32 v6, v3
	v_mul_f32_e64 v3, v150, -v91
	v_mul_f32_e64 v7, v149, -v176
	v_cndmask_b32_e64 v3, v3, v7, s[58:59]
	v_exp_f32_e32 v7, v3
	v_mul_f32_e64 v3, v152, -v91
	v_mul_f32_e64 v16, v151, -v176
	v_cndmask_b32_e32 v3, v3, v16, vcc
	v_exp_f32_e32 v16, v3
	v_mul_f32_e64 v3, v154, -v91
	v_mul_f32_e64 v17, v153, -v176
	v_cndmask_b32_e64 v3, v3, v17, s[76:77]
	v_exp_f32_e32 v17, v3
	v_cvt_pk_bf16_f32 v3, v4, v5
	v_mul_f32_e64 v4, v156, -v91
	v_mul_f32_e64 v5, v155, -v176
	ds_write2_b64 v165, v[0:1], v[2:3] offset1:2
	v_pk_mul_f32 v[0:1], v[6:7], v[8:9]
	v_cndmask_b32_e64 v4, v4, v5, s[6:7]
	v_mul_f32_e64 v5, v158, -v91
	v_mul_f32_e64 v6, v157, -v176
	v_cndmask_b32_e64 v5, v5, v6, s[8:9]
	v_mul_f32_e64 v6, v160, -v91
	v_mul_f32_e64 v7, v159, -v176
	v_cndmask_b32_e64 v6, v6, v7, s[68:69]
	v_mul_f32_e64 v7, v162, -v91
	v_mul_f32_e64 v8, v161, -v176
	v_cndmask_b32_e64 v7, v7, v8, s[70:71]
	v_exp_f32_e32 v4, v4
	v_exp_f32_e32 v5, v5
	v_exp_f32_e32 v6, v6
	v_exp_f32_e32 v7, v7
	v_pk_mul_f32 v[2:3], v[16:17], v[10:11]
	v_cvt_pk_bf16_f32 v0, v0, v1
	v_cvt_pk_bf16_f32 v1, v2, v3
	v_pk_mul_f32 v[2:3], v[4:5], v[12:13]
	v_pk_mul_f32 v[4:5], v[6:7], v[14:15]
	v_cvt_pk_bf16_f32 v2, v2, v3
	v_cvt_pk_bf16_f32 v3, v4, v5
	v_lshl_add_u32 v56, s2, 17, v95
	ds_write2_b64 v165, v[0:1], v[2:3] offset0:4 offset1:6
	s_waitcnt lgkmcnt(0)
	s_barrier
	global_load_dwordx4 v[0:3], v56, s[4:5]
	v_or_b32_e32 v4, 0x400, v56
	global_load_dwordx4 v[16:19], v4, s[4:5]
	v_or_b32_e32 v4, 0x800, v56
	global_load_dwordx4 v[20:23], v4, s[4:5]
	v_or_b32_e32 v4, 0xc00, v56
	global_load_dwordx4 v[24:27], v4, s[4:5]
	v_or_b32_e32 v4, 0x1000, v56
	global_load_dwordx4 v[48:51], v4, s[4:5]
	v_or_b32_e32 v4, 0x1400, v56
	global_load_dwordx4 v[52:55], v4, s[4:5]
	v_or_b32_e32 v4, 0x1800, v56
	global_load_dwordx4 v[58:61], v4, s[4:5]
	ds_read_b128 v[36:39], v166
	ds_read_b128 v[32:35], v166 offset:32
	s_waitcnt vmcnt(6) lgkmcnt(1)
	v_mfma_f32_32x32x16_bf16 v[0:15], v[0:3], v[36:39], 0
	v_or_b32_e32 v28, 0x1c00, v56
	global_load_dwordx4 v[62:65], v28, s[4:5]
	v_or_b32_e32 v78, s78, v92
	v_lshlrev_b32_e32 v28, 12, v78
	s_lshl_b32 s78, s94, 10
	v_add3_u32 v57, v163, s78, v28
	v_mbcnt_lo_u32_b32 v243, -1, 0
	v_mbcnt_hi_u32_b32 v243, -1, v243
	v_readlane_b32 s100, v255, 12
	v_and_b32_e32 v244, 31, v243
	v_lshrrev_b32_e32 v245, 5, v243
	v_lshrrev_b32_e32 v246, 2, v243
	v_and_b32_e32 v247, 3, v243
	v_mov_b32_e32 v248, s100
	v_mul_u32_u24_e32 v248, 36, v248
	v_add_u32_e32 v248, 0x1a000, v248
	v_mul_u32_u24_e32 v241, 0x48, v244
	v_lshl_add_u32 v241, v245, 3, v241
	v_add_u32_e32 v241, v248, v241
	v_mul_u32_u24_e32 v242, 0x48, v246
	v_lshl_add_u32 v242, v247, 4, v242
	v_add_u32_e32 v242, v248, v242
	v_sub_u32_e32 v240, v246, v244
	v_lshlrev_b32_e32 v240, 12, v240
	v_lshl_add_u32 v240, v247, 4, v240
	v_lshlrev_b32_e32 v245, 3, v245
	v_sub_u32_e32 v240, v240, v245
	v_add_u32_e32 v221, v57, v240
	global_load_dwordx4 v[224:227], v221, s[82:83]
	v_add_u32_e32 v222, 0x10000, v221
	global_load_dwordx4 v[228:231], v222, s[82:83]
	s_waitcnt vmcnt(7) lgkmcnt(0)
	v_mfma_f32_32x32x16_bf16 v[0:15], v[16:19], v[32:35], v[0:15]
	ds_read_b128 v[44:47], v166 offset:64
	ds_read_b128 v[40:43], v166 offset:96
	v_or_b32_e32 v79, 16, v57
	v_or_b32_e32 v167, 32, v57
	v_or_b32_e32 v176, 48, v57
	v_or_b32_e32 v66, 0x2000, v56
	s_waitcnt vmcnt(7) lgkmcnt(1)
	v_mfma_f32_32x32x16_bf16 v[0:15], v[20:23], v[44:47], v[0:15]
	v_or_b32_e32 v70, 0x2400, v56
	v_or_b32_e32 v194, 64, v57
	v_or_b32_e32 v195, 0x50, v57
	v_or_b32_e32 v196, 0x60, v57
	v_or_b32_e32 v197, 0x70, v57
	s_waitcnt vmcnt(6) lgkmcnt(0)
	v_mfma_f32_32x32x16_bf16 v[0:15], v[24:27], v[40:43], v[0:15]
	ds_read_b128 v[16:19], v166 offset:128
	ds_read_b128 v[20:23], v166 offset:160
	ds_read_b128 v[24:27], v166 offset:192
	ds_read_b128 v[28:31], v166 offset:224
	s_nop 0
	global_load_dwordx4 v[66:69], v66, s[4:5]
	s_nop 0
	global_load_dwordx4 v[70:73], v70, s[4:5]
	s_waitcnt vmcnt(7) lgkmcnt(3)
	v_mfma_f32_32x32x16_bf16 v[0:15], v[48:51], v[16:19], v[0:15]
	v_or_b32_e32 v48, 0x2800, v56
	v_or_b32_e32 v49, 0x2c00, v56
	global_load_dwordx4 v[80:83], v48, s[4:5]
	global_load_dwordx4 v[84:87], v49, s[4:5]
	v_or_b32_e32 v48, 0x3000, v56
	v_or_b32_e32 v49, 0x3400, v56
	s_waitcnt vmcnt(8) lgkmcnt(2)
; DI unsigned cvt_pk_bf16(float lo, float hi) { unsigned r; asm volatile("v_cvt_pk_bf16_f32 %0, %1, %2" : "=v"(r) : "v"(lo), "v"(hi)); return r; }
; DI float bf_lo(unsigned w) { return __uint_as_float(w << 16); }
; DI float bf_hi(unsigned w) { return __uint_as_float(w & 0xffff0000u); }
; #define MFMA32(a, b, c) __builtin_amdgcn_mfma_f32_32x32x16_bf16((a), (b), (c), 0, 0, 0)
; template <bool DRY, bool H1>
; DI void intra_phase(LAS unsigned char* lds, const Params& p) {
;     ...
;       for (int t = 0; t < 8; ++t) {
;         if (t < 7) {
; #pragma unroll
;           for (int s = 0; s < 8; ++s) va[(t + 1) & 1][s] = ldg16(vT, vo + (unsigned)(t + 1) * 8192u + 1024u * s);
; #pragma unroll
;           for (int gq = 0; gq < 4; ++gq) { yold[(t + 1) & 1][gq] = *(const u32x2*)((const char*)y + (yo + 64u * (t + 1) + 16u * gq)); if constexpr (H1) yol2[(t + 1) & 1][gq] = *(const u32x2*)((const char*)yb + (yo + 64u * (t + 1) + 16u * gq)); }
;         }
;         f32x16 yt;
; #pragma unroll
;         for (int i = 0; i < 16; ++i) yt[i] = 0.f;
; #pragma unroll
;         for (int s = 0; s < 8; ++s) yt = MFMA32(va[t & 1][s], pf[s], yt);
; #pragma unroll
;         for (int gq = 0; gq < 4; ++gq) {
;           const u32x2 ov = yold[t & 1][gq], o2 = yol2[t & 1][gq];
;           const float v0 = bf_lo(ov.x) + bf_lo(o2.x) + yt[4 * gq], v1 = bf_hi(ov.x) + bf_hi(o2.x) + yt[4 * gq + 1], v2 = bf_lo(ov.y) + bf_lo(o2.y) + yt[4 * gq + 2], v3 = bf_hi(ov.y) + bf_hi(o2.y) + yt[4 * gq + 3];
;           sq2 += v0 * v0 + v1 * v1 + v2 * v2 + v3 * v3;
;           u32x2 a; a.x = cvt_pk_bf16(v0, v1); a.y = cvt_pk_bf16(v2, v3); if (!DRY || v0 == 12345.678f) *(u32x2*)((char*)y + (yo + 64u * t + 16u * gq)) = a;
;         }
;         __builtin_amdgcn_sched_barrier(0);
;       }
	v_mfma_f32_32x32x16_bf16 v[0:15], v[52:55], v[20:23], v[0:15]
	global_load_dwordx4 v[52:55], v48, s[4:5]
	global_load_dwordx4 v[88:91], v49, s[4:5]
	v_or_b32_e32 v48, 0x3800, v56
	v_or_b32_e32 v49, 0x3c00, v56
	global_load_dwordx4 v[168:171], v48, s[4:5]
	global_load_dwordx4 v[172:175], v49, s[4:5]
	v_add_u32_e32 v221, v194, v240
	global_load_dwordx4 v[232:235], v221, s[82:83]
	v_add_u32_e32 v222, 0x10000, v221
	global_load_dwordx4 v[236:239], v222, s[82:83]
	s_waitcnt vmcnt(10)
	s_waitcnt vmcnt(10)
	ds_write_b128 v242, v[224:227]
	ds_write_b128 v242, v[228:231] offset:1152
	s_waitcnt lgkmcnt(0)
	ds_read_b64 v[74:75], v241
	ds_read_b64 v[178:179], v241 offset:16
	ds_read_b64 v[180:181], v241 offset:32
	ds_read_b64 v[182:183], v241 offset:48
	s_waitcnt lgkmcnt(0)
	v_lshlrev_b32_e32 v48, 16, v74
	s_waitcnt lgkmcnt(1)
	v_mfma_f32_32x32x16_bf16 v[0:15], v[58:61], v[24:27], v[0:15]
	v_add_f32_e32 v48, 0, v48
	s_waitcnt lgkmcnt(0)
	v_mfma_f32_32x32x16_bf16 v[0:15], v[62:65], v[28:31], v[0:15]
	s_nop 11
	v_add_f32_e32 v0, v48, v0
	v_and_b32_e32 v48, 0xffff0000, v74
	v_add_f32_e32 v48, 0, v48
	v_add_f32_e32 v1, v48, v1
	v_lshlrev_b32_e32 v48, 16, v75
	v_add_f32_e32 v48, 0, v48
	v_add_f32_e32 v2, v48, v2
	v_and_b32_e32 v48, 0xffff0000, v75
	v_add_f32_e32 v48, 0, v48
	v_add_f32_e32 v3, v48, v3
	v_mul_f32_e32 v48, v1, v1
	v_fmac_f32_e32 v48, v0, v0
	v_cvt_pk_bf16_f32 v0, v0, v1
	v_cvt_pk_bf16_f32 v1, v2, v3
	v_add_u32_e32 v252, v57, v240
	ds_write_b64 v241, v[0:1]
	s_waitcnt vmcnt(10)
	v_and_b32_e32 v1, 0xffff0000, v178
	v_fmac_f32_e32 v48, v2, v2
	v_lshlrev_b32_e32 v0, 16, v178
	v_add_f32_e32 v1, 0, v1
	v_fmac_f32_e32 v48, v3, v3
	v_add_f32_e32 v0, 0, v0
	v_add_f32_e32 v1, v1, v5
	v_lshlrev_b32_e32 v2, 16, v179
	v_and_b32_e32 v3, 0xffff0000, v179
	v_add_f32_e32 v0, v0, v4
	v_add_f32_e32 v2, 0, v2
	v_add_f32_e32 v3, 0, v3
	v_mul_f32_e32 v4, v1, v1
	v_add_f32_e32 v2, v2, v6
	v_add_f32_e32 v3, v3, v7
	v_fmac_f32_e32 v4, v0, v0
	v_cvt_pk_bf16_f32 v0, v0, v1
	v_cvt_pk_bf16_f32 v1, v2, v3
	ds_write_b64 v241, v[0:1] offset:16
	s_waitcnt vmcnt(10)
	v_and_b32_e32 v1, 0xffff0000, v180
	v_fmac_f32_e32 v4, v2, v2
	v_lshlrev_b32_e32 v0, 16, v180
	v_add_f32_e32 v1, 0, v1
	v_fmac_f32_e32 v4, v3, v3
	v_add_f32_e32 v0, 0, v0
	v_add_f32_e32 v1, v1, v9
	v_lshlrev_b32_e32 v2, 16, v181
	v_and_b32_e32 v3, 0xffff0000, v181
	v_add_f32_e32 v0, v0, v8
	v_add_f32_e32 v2, 0, v2
	v_add_f32_e32 v3, 0, v3
	v_mul_f32_e32 v5, v1, v1
	v_add_f32_e32 v2, v2, v10
	v_add_f32_e32 v3, v3, v11
	v_fmac_f32_e32 v5, v0, v0
	v_cvt_pk_bf16_f32 v0, v0, v1
	v_cvt_pk_bf16_f32 v1, v2, v3
	ds_write_b64 v241, v[0:1] offset:32
	s_waitcnt vmcnt(10)
	v_and_b32_e32 v1, 0xffff0000, v182
	v_fmac_f32_e32 v5, v2, v2
	v_lshlrev_b32_e32 v0, 16, v182
	v_add_f32_e32 v1, 0, v1
	v_add_f32_e32 v4, v48, v4
	v_fmac_f32_e32 v5, v3, v3
	v_add_f32_e32 v0, 0, v0
	v_add_f32_e32 v1, v1, v13
	v_lshlrev_b32_e32 v2, 16, v183
	v_add_f32_e32 v4, v5, v4
	v_add_f32_e32 v0, v0, v12
	v_add_f32_e32 v2, 0, v2
	v_and_b32_e32 v3, 0xffff0000, v183
	v_mul_f32_e32 v5, v1, v1
	v_add_f32_e32 v2, v2, v14
	v_add_f32_e32 v3, 0, v3
	v_fmac_f32_e32 v5, v0, v0
	v_add_f32_e32 v3, v3, v15
	v_fmac_f32_e32 v5, v2, v2
	v_fmac_f32_e32 v5, v3, v3
	v_add_f32_e32 v79, v5, v4
	v_cvt_pk_bf16_f32 v0, v0, v1
	v_cvt_pk_bf16_f32 v1, v2, v3
	ds_write_b64 v241, v[0:1] offset:48
	s_waitcnt lgkmcnt(0)
	ds_read_b128 v[244:247], v242
	ds_read_b128 v[248:251], v242 offset:1152
	v_add_u32_e32 v253, 0x10000, v252
	s_waitcnt lgkmcnt(0)
	global_store_dwordx4 v252, v[244:247], s[82:83]
	global_store_dwordx4 v253, v[248:251], s[82:83]
	s_nop 1
	s_waitcnt vmcnt(11)
	v_mfma_f32_32x32x16_bf16 v[0:15], v[66:69], v[36:39], 0
	v_or_b32_e32 v48, 0x4000, v56
	v_or_b32_e32 v49, 0x4400, v56
	v_or_b32_e32 v66, 0x4800, v56
	global_load_dwordx4 v[58:61], v48, s[4:5]
	global_load_dwordx4 v[62:65], v49, s[4:5]
	v_or_b32_e32 v48, 0x4c00, v56
	v_or_b32_e32 v49, 0x5400, v56
	v_or_b32_e32 v167, 0x80, v57
	s_waitcnt vmcnt(12)
	v_mfma_f32_32x32x16_bf16 v[0:15], v[70:73], v[32:35], v[0:15]
	global_load_dwordx4 v[66:69], v66, s[4:5]
	s_nop 0
	global_load_dwordx4 v[70:73], v48, s[4:5]
	v_or_b32_e32 v48, 0x5000, v56
	v_or_b32_e32 v176, 0x90, v57
	v_or_b32_e32 v198, 0xa0, v57
	v_or_b32_e32 v199, 0xb0, v57
	s_waitcnt vmcnt(13)
	v_mfma_f32_32x32x16_bf16 v[0:15], v[80:83], v[44:47], v[0:15]
	global_load_dwordx4 v[80:83], v48, s[4:5]
	global_load_dwordx4 v[178:181], v49, s[4:5]
	v_or_b32_e32 v48, 0x5800, v56
	v_or_b32_e32 v49, 0x5c00, v56
	s_waitcnt vmcnt(14)
	v_mfma_f32_32x32x16_bf16 v[0:15], v[84:87], v[40:43], v[0:15]
	global_load_dwordx4 v[84:87], v48, s[4:5]
	global_load_dwordx4 v[182:185], v49, s[4:5]
	s_waitcnt vmcnt(15)
	v_mfma_f32_32x32x16_bf16 v[0:15], v[52:55], v[16:19], v[0:15]
	v_add_u32_e32 v221, v167, v240
	global_load_dwordx4 v[224:227], v221, s[82:83]
	v_add_u32_e32 v222, 0x10000, v221
	global_load_dwordx4 v[228:231], v222, s[82:83]
	s_waitcnt vmcnt(12)
	s_waitcnt vmcnt(12)
	ds_write_b128 v242, v[232:235]
	ds_write_b128 v242, v[236:239] offset:1152
	s_waitcnt lgkmcnt(0)
	ds_read_b64 v[186:187], v241
	ds_read_b64 v[188:189], v241 offset:16
	ds_read_b64 v[190:191], v241 offset:32
	ds_read_b64 v[50:51], v241 offset:48
	s_waitcnt lgkmcnt(0)
	v_lshlrev_b32_e32 v54, 16, v186
	v_and_b32_e32 v55, 0xffff0000, v186
	v_add_f32_e32 v54, 0, v54
	v_add_f32_e32 v55, 0, v55
	v_mfma_f32_32x32x16_bf16 v[0:15], v[88:91], v[20:23], v[0:15]
	v_lshlrev_b32_e32 v88, 16, v187
	v_and_b32_e32 v89, 0xffff0000, v187
	v_add_f32_e32 v88, 0, v88
	s_waitcnt vmcnt(12)
; DI unsigned cvt_pk_bf16(float lo, float hi) { unsigned r; asm volatile("v_cvt_pk_bf16_f32 %0, %1, %2" : "=v"(r) : "v"(lo), "v"(hi)); return r; }
; DI float bf_lo(unsigned w) { return __uint_as_float(w << 16); }
; DI float bf_hi(unsigned w) { return __uint_as_float(w & 0xffff0000u); }
; #define MFMA32(a, b, c) __builtin_amdgcn_mfma_f32_32x32x16_bf16((a), (b), (c), 0, 0, 0)
; template <bool DRY, bool H1>
; DI void intra_phase(LAS unsigned char* lds, const Params& p) {
;     ...
;       for (int t = 0; t < 8; ++t) {
;         if (t < 7) {
; #pragma unroll
;           for (int s = 0; s < 8; ++s) va[(t + 1) & 1][s] = ldg16(vT, vo + (unsigned)(t + 1) * 8192u + 1024u * s);
; #pragma unroll
;           for (int gq = 0; gq < 4; ++gq) { yold[(t + 1) & 1][gq] = *(const u32x2*)((const char*)y + (yo + 64u * (t + 1) + 16u * gq)); if constexpr (H1) yol2[(t + 1) & 1][gq] = *(const u32x2*)((const char*)yb + (yo + 64u * (t + 1) + 16u * gq)); }
;         }
;         f32x16 yt;
; #pragma unroll
;         for (int i = 0; i < 16; ++i) yt[i] = 0.f;
; #pragma unroll
;         for (int s = 0; s < 8; ++s) yt = MFMA32(va[t & 1][s], pf[s], yt);
; #pragma unroll
;         for (int gq = 0; gq < 4; ++gq) {
;           const u32x2 ov = yold[t & 1][gq], o2 = yol2[t & 1][gq];
;           const float v0 = bf_lo(ov.x) + bf_lo(o2.x) + yt[4 * gq], v1 = bf_hi(ov.x) + bf_hi(o2.x) + yt[4 * gq + 1], v2 = bf_lo(ov.y) + bf_lo(o2.y) + yt[4 * gq + 2], v3 = bf_hi(ov.y) + bf_hi(o2.y) + yt[4 * gq + 3];
;           sq2 += v0 * v0 + v1 * v1 + v2 * v2 + v3 * v3;
;           u32x2 a; a.x = cvt_pk_bf16(v0, v1); a.y = cvt_pk_bf16(v2, v3); if (!DRY || v0 == 12345.678f) *(u32x2*)((char*)y + (yo + 64u * t + 16u * gq)) = a;
;         }
;         __builtin_amdgcn_sched_barrier(0);
;       }
	v_lshlrev_b32_e32 v90, 16, v188
	v_add_f32_e32 v89, 0, v89
	v_and_b32_e32 v91, 0xffff0000, v188
	v_add_f32_e32 v90, 0, v90
	v_mfma_f32_32x32x16_bf16 v[0:15], v[168:171], v[24:27], v[0:15]
	v_lshlrev_b32_e32 v168, 16, v189
	v_and_b32_e32 v169, 0xffff0000, v189
	v_add_f32_e32 v91, 0, v91
	v_add_f32_e32 v168, 0, v168
	v_add_f32_e32 v169, 0, v169
	v_mfma_f32_32x32x16_bf16 v[0:15], v[172:175], v[28:31], v[0:15]
	s_nop 11
	v_add_f32_e32 v54, v54, v0
	v_add_f32_e32 v0, v55, v1
	v_add_f32_e32 v2, v88, v2
	v_add_f32_e32 v3, v89, v3
	v_mul_f32_e32 v55, v0, v0
	v_cvt_pk_bf16_f32 v0, v54, v0
	v_cvt_pk_bf16_f32 v1, v2, v3
	v_add_f32_e32 v4, v90, v4
	v_add_f32_e32 v5, v91, v5
	v_add_f32_e32 v6, v168, v6
	v_add_f32_e32 v7, v169, v7
	v_add_u32_e32 v252, v194, v240
	ds_write_b64 v241, v[0:1]
	v_cvt_pk_bf16_f32 v0, v4, v5
	v_cvt_pk_bf16_f32 v1, v6, v7
	v_fmac_f32_e32 v55, v54, v54
	ds_write_b64 v241, v[0:1] offset:16
	s_waitcnt vmcnt(12)
	v_and_b32_e32 v1, 0xffff0000, v190
	v_mul_f32_e32 v88, v5, v5
	v_fmac_f32_e32 v55, v2, v2
	v_lshlrev_b32_e32 v0, 16, v190
	v_add_f32_e32 v1, 0, v1
	v_fmac_f32_e32 v88, v4, v4
	v_fmac_f32_e32 v55, v3, v3
	v_add_f32_e32 v0, 0, v0
	v_add_f32_e32 v1, v1, v9
	v_lshlrev_b32_e32 v3, 16, v191
	v_and_b32_e32 v4, 0xffff0000, v191
	v_add_f32_e32 v0, v0, v8
	v_add_f32_e32 v3, 0, v3
	v_add_f32_e32 v4, 0, v4
	v_mul_f32_e32 v5, v1, v1
	v_add_f32_e32 v3, v3, v10
	v_add_f32_e32 v4, v4, v11
	v_fmac_f32_e32 v5, v0, v0
	v_cvt_pk_bf16_f32 v0, v0, v1
	v_cvt_pk_bf16_f32 v1, v3, v4
	v_fmac_f32_e32 v88, v6, v6
	ds_write_b64 v241, v[0:1] offset:32
	s_waitcnt vmcnt(12)
	v_and_b32_e32 v1, 0xffff0000, v50
	v_fmac_f32_e32 v88, v7, v7
	v_add_f32_e32 v2, v79, v55
	v_fmac_f32_e32 v5, v3, v3
	v_lshlrev_b32_e32 v0, 16, v50
	v_add_f32_e32 v1, 0, v1
	v_add_f32_e32 v2, v88, v2
	v_fmac_f32_e32 v5, v4, v4
	v_add_f32_e32 v0, 0, v0
	v_add_f32_e32 v1, v1, v13
	v_lshlrev_b32_e32 v3, 16, v51
	v_add_f32_e32 v2, v5, v2
	v_add_f32_e32 v0, v0, v12
	v_add_f32_e32 v3, 0, v3
	v_and_b32_e32 v4, 0xffff0000, v51
	v_mul_f32_e32 v5, v1, v1
	v_add_f32_e32 v3, v3, v14
	v_add_f32_e32 v4, 0, v4
	v_fmac_f32_e32 v5, v0, v0
	v_add_f32_e32 v4, v4, v15
	v_fmac_f32_e32 v5, v3, v3
	v_fmac_f32_e32 v5, v4, v4
	v_add_f32_e32 v79, v5, v2
	v_cvt_pk_bf16_f32 v0, v0, v1
	v_cvt_pk_bf16_f32 v1, v3, v4
	ds_write_b64 v241, v[0:1] offset:48
	s_waitcnt lgkmcnt(0)
	ds_read_b128 v[244:247], v242
	ds_read_b128 v[248:251], v242 offset:1152
	v_add_u32_e32 v253, 0x10000, v252
	s_waitcnt lgkmcnt(0)
	global_store_dwordx4 v252, v[244:247], s[82:83]
	global_store_dwordx4 v253, v[248:251], s[82:83]
	s_nop 1
	s_waitcnt vmcnt(11)
	v_mfma_f32_32x32x16_bf16 v[0:15], v[58:61], v[36:39], 0
	v_or_b32_e32 v50, 0x6000, v56
	v_or_b32_e32 v51, 0x6400, v56
	v_or_b32_e32 v54, 0x6800, v56
	v_or_b32_e32 v196, 0xc0, v57
	v_or_b32_e32 v197, 0xd0, v57
	v_or_b32_e32 v200, 0xe0, v57
	v_or_b32_e32 v201, 0xf0, v57
	s_waitcnt vmcnt(10)
	v_mfma_f32_32x32x16_bf16 v[0:15], v[62:65], v[32:35], v[0:15]
	global_load_dwordx4 v[58:61], v50, s[4:5]
	global_load_dwordx4 v[62:65], v51, s[4:5]
	v_or_b32_e32 v50, 0x6c00, v56
	v_or_b32_e32 v51, 0x7400, v56
	s_waitcnt vmcnt(11)
	v_mfma_f32_32x32x16_bf16 v[0:15], v[66:69], v[44:47], v[0:15]
	global_load_dwordx4 v[66:69], v54, s[4:5]
	global_load_dwordx4 v[88:91], v50, s[4:5]
	v_or_b32_e32 v50, 0x7000, v56
	global_load_dwordx4 v[168:171], v50, s[4:5]
	global_load_dwordx4 v[172:175], v51, s[4:5]
	v_or_b32_e32 v50, 0x7800, v56
	v_or_b32_e32 v51, 0x7c00, v56
	s_waitcnt vmcnt(14)
	v_mfma_f32_32x32x16_bf16 v[0:15], v[70:73], v[40:43], v[0:15]
	global_load_dwordx4 v[70:73], v50, s[4:5]
	global_load_dwordx4 v[186:189], v51, s[4:5]
	v_add_u32_e32 v221, v196, v240
	global_load_dwordx4 v[232:235], v221, s[82:83]
	v_add_u32_e32 v222, 0x10000, v221
	global_load_dwordx4 v[236:239], v222, s[82:83]
	s_nop 0
	s_waitcnt vmcnt(17)
	v_mfma_f32_32x32x16_bf16 v[0:15], v[80:83], v[16:19], v[0:15]
	s_waitcnt vmcnt(12)
	s_waitcnt vmcnt(12)
	ds_write_b128 v242, v[224:227]
	ds_write_b128 v242, v[228:231] offset:1152
	s_waitcnt lgkmcnt(0)
	ds_read_b64 v[74:75], v241
	ds_read_b64 v[192:193], v241 offset:16
	ds_read_b64 v[52:53], v241 offset:32
	ds_read_b64 v[48:49], v241 offset:48
	s_waitcnt lgkmcnt(0)
	v_lshlrev_b32_e32 v80, 16, v74
	v_and_b32_e32 v74, 0xffff0000, v74
	v_add_f32_e32 v80, 0, v80
	v_add_f32_e32 v74, 0, v74
	v_lshlrev_b32_e32 v81, 16, v75
	v_and_b32_e32 v75, 0xffff0000, v75
	v_add_f32_e32 v81, 0, v81
	v_mfma_f32_32x32x16_bf16 v[0:15], v[178:181], v[20:23], v[0:15]
	s_waitcnt vmcnt(12)
	v_lshlrev_b32_e32 v82, 16, v192
	v_add_f32_e32 v75, 0, v75
	v_and_b32_e32 v83, 0xffff0000, v192
	v_add_f32_e32 v82, 0, v82
	v_add_f32_e32 v83, 0, v83
	v_mfma_f32_32x32x16_bf16 v[0:15], v[84:87], v[24:27], v[0:15]
	v_lshlrev_b32_e32 v84, 16, v193
	v_and_b32_e32 v85, 0xffff0000, v193
	v_add_f32_e32 v84, 0, v84
	v_add_f32_e32 v85, 0, v85
	v_mfma_f32_32x32x16_bf16 v[0:15], v[182:185], v[28:31], v[0:15]
	s_nop 11
	v_add_f32_e32 v80, v80, v0
	v_add_f32_e32 v0, v74, v1
	v_add_f32_e32 v2, v81, v2
	v_add_f32_e32 v3, v75, v3
	v_mul_f32_e32 v74, v0, v0
	v_cvt_pk_bf16_f32 v0, v80, v0
	v_cvt_pk_bf16_f32 v1, v2, v3
	v_add_f32_e32 v4, v82, v4
	v_add_f32_e32 v5, v83, v5
	v_add_f32_e32 v6, v84, v6
	v_add_f32_e32 v7, v85, v7
	v_add_u32_e32 v252, v167, v240
	ds_write_b64 v241, v[0:1]
	v_cvt_pk_bf16_f32 v0, v4, v5
	v_cvt_pk_bf16_f32 v1, v6, v7
	v_fmac_f32_e32 v74, v80, v80
	ds_write_b64 v241, v[0:1] offset:16
	s_waitcnt vmcnt(12)
; DI unsigned cvt_pk_bf16(float lo, float hi) { unsigned r; asm volatile("v_cvt_pk_bf16_f32 %0, %1, %2" : "=v"(r) : "v"(lo), "v"(hi)); return r; }
; DI float bf_lo(unsigned w) { return __uint_as_float(w << 16); }
; DI float bf_hi(unsigned w) { return __uint_as_float(w & 0xffff0000u); }
; #define MFMA32(a, b, c) __builtin_amdgcn_mfma_f32_32x32x16_bf16((a), (b), (c), 0, 0, 0)
; template <bool DRY, bool H1>
; DI void intra_phase(LAS unsigned char* lds, const Params& p) {
;     ...
;       for (int t = 0; t < 8; ++t) {
;         if (t < 7) {
; #pragma unroll
;           for (int s = 0; s < 8; ++s) va[(t + 1) & 1][s] = ldg16(vT, vo + (unsigned)(t + 1) * 8192u + 1024u * s);
; #pragma unroll
;           for (int gq = 0; gq < 4; ++gq) { yold[(t + 1) & 1][gq] = *(const u32x2*)((const char*)y + (yo + 64u * (t + 1) + 16u * gq)); if constexpr (H1) yol2[(t + 1) & 1][gq] = *(const u32x2*)((const char*)yb + (yo + 64u * (t + 1) + 16u * gq)); }
;         }
;         f32x16 yt;
; #pragma unroll
;         for (int i = 0; i < 16; ++i) yt[i] = 0.f;
; #pragma unroll
;         for (int s = 0; s < 8; ++s) yt = MFMA32(va[t & 1][s], pf[s], yt);
; #pragma unroll
;         for (int gq = 0; gq < 4; ++gq) {
;           const u32x2 ov = yold[t & 1][gq], o2 = yol2[t & 1][gq];
;           const float v0 = bf_lo(ov.x) + bf_lo(o2.x) + yt[4 * gq], v1 = bf_hi(ov.x) + bf_hi(o2.x) + yt[4 * gq + 1], v2 = bf_lo(ov.y) + bf_lo(o2.y) + yt[4 * gq + 2], v3 = bf_hi(ov.y) + bf_hi(o2.y) + yt[4 * gq + 3];
;           sq2 += v0 * v0 + v1 * v1 + v2 * v2 + v3 * v3;
;           u32x2 a; a.x = cvt_pk_bf16(v0, v1); a.y = cvt_pk_bf16(v2, v3); if (!DRY || v0 == 12345.678f) *(u32x2*)((char*)y + (yo + 64u * t + 16u * gq)) = a;
;         }
;         __builtin_amdgcn_sched_barrier(0);
;       }
	v_and_b32_e32 v1, 0xffff0000, v52
	v_mul_f32_e32 v75, v5, v5
	v_fmac_f32_e32 v74, v2, v2
	v_lshlrev_b32_e32 v0, 16, v52
	v_add_f32_e32 v1, 0, v1
	v_fmac_f32_e32 v75, v4, v4
	v_fmac_f32_e32 v74, v3, v3
	v_add_f32_e32 v0, 0, v0
	v_add_f32_e32 v1, v1, v9
	v_lshlrev_b32_e32 v3, 16, v53
	v_and_b32_e32 v4, 0xffff0000, v53
	v_add_f32_e32 v0, v0, v8
	v_add_f32_e32 v3, 0, v3
	v_add_f32_e32 v4, 0, v4
	v_mul_f32_e32 v5, v1, v1
	v_add_f32_e32 v3, v3, v10
	v_add_f32_e32 v4, v4, v11
	v_fmac_f32_e32 v5, v0, v0
	v_cvt_pk_bf16_f32 v0, v0, v1
	v_cvt_pk_bf16_f32 v1, v3, v4
	v_fmac_f32_e32 v75, v6, v6
	ds_write_b64 v241, v[0:1] offset:32
	s_waitcnt vmcnt(12)
	v_and_b32_e32 v1, 0xffff0000, v48
	v_fmac_f32_e32 v75, v7, v7
	v_add_f32_e32 v2, v79, v74
	v_fmac_f32_e32 v5, v3, v3
	v_lshlrev_b32_e32 v0, 16, v48
	v_add_f32_e32 v1, 0, v1
	v_add_f32_e32 v2, v75, v2
	v_fmac_f32_e32 v5, v4, v4
	v_add_f32_e32 v0, 0, v0
	v_add_f32_e32 v1, v1, v13
	v_lshlrev_b32_e32 v3, 16, v49
	v_add_f32_e32 v2, v5, v2
	v_add_f32_e32 v0, v0, v12
	v_add_f32_e32 v3, 0, v3
	v_and_b32_e32 v4, 0xffff0000, v49
	v_mul_f32_e32 v5, v1, v1
	v_add_f32_e32 v3, v3, v14
	v_add_f32_e32 v4, 0, v4
	v_fmac_f32_e32 v5, v0, v0
	v_add_f32_e32 v4, v4, v15
	v_fmac_f32_e32 v5, v3, v3
	v_fmac_f32_e32 v5, v4, v4
	v_add_f32_e32 v79, v5, v2
	v_cvt_pk_bf16_f32 v0, v0, v1
	v_cvt_pk_bf16_f32 v1, v3, v4
	ds_write_b64 v241, v[0:1] offset:48
	s_waitcnt lgkmcnt(0)
	ds_read_b128 v[244:247], v242
	ds_read_b128 v[248:251], v242 offset:1152
	v_add_u32_e32 v253, 0x10000, v252
	s_waitcnt lgkmcnt(0)
	global_store_dwordx4 v252, v[244:247], s[82:83]
	global_store_dwordx4 v253, v[248:251], s[82:83]
	s_nop 1
	s_waitcnt vmcnt(11)
	v_mfma_f32_32x32x16_bf16 v[0:15], v[58:61], v[36:39], 0
	v_or_b32_e32 v48, 0x8000, v56
	v_or_b32_e32 v49, 0x8400, v56
	v_or_b32_e32 v52, 0x8800, v56
	v_or_b32_e32 v167, 0x100, v57
	v_or_b32_e32 v176, 0x110, v57
	v_or_b32_e32 v203, 0x120, v57
	v_or_b32_e32 v204, 0x130, v57
	s_waitcnt vmcnt(10)
	v_mfma_f32_32x32x16_bf16 v[0:15], v[62:65], v[32:35], v[0:15]
	global_load_dwordx4 v[58:61], v48, s[4:5]
	global_load_dwordx4 v[62:65], v49, s[4:5]
	v_or_b32_e32 v48, 0x8c00, v56
	v_or_b32_e32 v49, 0x9400, v56
	s_waitcnt vmcnt(11)
	v_mfma_f32_32x32x16_bf16 v[0:15], v[66:69], v[44:47], v[0:15]
	global_load_dwordx4 v[66:69], v52, s[4:5]
	global_load_dwordx4 v[80:83], v48, s[4:5]
	v_or_b32_e32 v48, 0x9000, v56
	global_load_dwordx4 v[84:87], v48, s[4:5]
	global_load_dwordx4 v[178:181], v49, s[4:5]
	v_or_b32_e32 v48, 0x9800, v56
	v_or_b32_e32 v49, 0x9c00, v56
	s_waitcnt vmcnt(14)
	v_mfma_f32_32x32x16_bf16 v[0:15], v[88:91], v[40:43], v[0:15]
	global_load_dwordx4 v[88:91], v48, s[4:5]
	global_load_dwordx4 v[182:185], v49, s[4:5]
	v_add_u32_e32 v221, v167, v240
	global_load_dwordx4 v[224:227], v221, s[82:83]
	v_add_u32_e32 v222, 0x10000, v221
	global_load_dwordx4 v[228:231], v222, s[82:83]
	s_nop 0
	s_waitcnt vmcnt(17)
	v_mfma_f32_32x32x16_bf16 v[0:15], v[168:171], v[16:19], v[0:15]
	s_waitcnt vmcnt(12)
	s_waitcnt vmcnt(12)
	ds_write_b128 v242, v[232:235]
	ds_write_b128 v242, v[236:239] offset:1152
	s_waitcnt lgkmcnt(0)
	ds_read_b64 v[190:191], v241
	ds_read_b64 v[194:195], v241 offset:16
	ds_read_b64 v[54:55], v241 offset:32
	ds_read_b64 v[50:51], v241 offset:48
	s_waitcnt lgkmcnt(0)
	v_lshlrev_b32_e32 v168, 16, v190
	v_and_b32_e32 v169, 0xffff0000, v190
	v_add_f32_e32 v168, 0, v168
	v_add_f32_e32 v169, 0, v169
	v_lshlrev_b32_e32 v170, 16, v191
	v_and_b32_e32 v171, 0xffff0000, v191
	v_add_f32_e32 v170, 0, v170
	v_mfma_f32_32x32x16_bf16 v[0:15], v[172:175], v[20:23], v[0:15]
	s_waitcnt vmcnt(12)
	v_lshlrev_b32_e32 v172, 16, v194
	v_add_f32_e32 v171, 0, v171
	v_mfma_f32_32x32x16_bf16 v[0:15], v[70:73], v[24:27], v[0:15]
	v_add_f32_e32 v70, 0, v172
	v_and_b32_e32 v71, 0xffff0000, v194
	v_lshlrev_b32_e32 v72, 16, v195
	v_and_b32_e32 v73, 0xffff0000, v195
	v_add_f32_e32 v71, 0, v71
	v_add_f32_e32 v72, 0, v72
	v_add_f32_e32 v73, 0, v73
	v_mfma_f32_32x32x16_bf16 v[0:15], v[186:189], v[28:31], v[0:15]
	s_nop 11
	v_add_f32_e32 v168, v168, v0
	v_add_f32_e32 v0, v169, v1
	v_add_f32_e32 v2, v170, v2
	v_add_f32_e32 v3, v171, v3
	v_add_f32_e32 v4, v70, v4
	v_mul_f32_e32 v70, v0, v0
	v_cvt_pk_bf16_f32 v0, v168, v0
	v_cvt_pk_bf16_f32 v1, v2, v3
	v_add_f32_e32 v5, v71, v5
	v_add_f32_e32 v6, v72, v6
	v_add_f32_e32 v7, v73, v7
	v_add_u32_e32 v252, v196, v240
	ds_write_b64 v241, v[0:1]
	v_cvt_pk_bf16_f32 v0, v4, v5
	v_cvt_pk_bf16_f32 v1, v6, v7
	v_fmac_f32_e32 v70, v168, v168
	ds_write_b64 v241, v[0:1] offset:16
	s_waitcnt vmcnt(12)
	v_and_b32_e32 v1, 0xffff0000, v54
	v_mul_f32_e32 v71, v5, v5
	v_fmac_f32_e32 v70, v2, v2
	v_lshlrev_b32_e32 v0, 16, v54
	v_add_f32_e32 v1, 0, v1
	v_fmac_f32_e32 v71, v4, v4
	v_fmac_f32_e32 v70, v3, v3
	v_add_f32_e32 v0, 0, v0
	v_add_f32_e32 v1, v1, v9
	v_lshlrev_b32_e32 v3, 16, v55
	v_and_b32_e32 v4, 0xffff0000, v55
	v_add_f32_e32 v0, v0, v8
	v_add_f32_e32 v3, 0, v3
	v_add_f32_e32 v4, 0, v4
	v_mul_f32_e32 v5, v1, v1
	v_add_f32_e32 v3, v3, v10
	v_add_f32_e32 v4, v4, v11
	v_fmac_f32_e32 v5, v0, v0
	v_cvt_pk_bf16_f32 v0, v0, v1
	v_cvt_pk_bf16_f32 v1, v3, v4
	v_fmac_f32_e32 v71, v6, v6
	ds_write_b64 v241, v[0:1] offset:32
	s_waitcnt vmcnt(12)
	v_and_b32_e32 v1, 0xffff0000, v50
	v_fmac_f32_e32 v71, v7, v7
	v_add_f32_e32 v2, v79, v70
	v_fmac_f32_e32 v5, v3, v3
	v_lshlrev_b32_e32 v0, 16, v50
	v_add_f32_e32 v1, 0, v1
	v_add_f32_e32 v2, v71, v2
	v_fmac_f32_e32 v5, v4, v4
	v_add_f32_e32 v0, 0, v0
	v_add_f32_e32 v1, v1, v13
	v_lshlrev_b32_e32 v3, 16, v51
	v_add_f32_e32 v2, v5, v2
	v_add_f32_e32 v0, v0, v12
	v_add_f32_e32 v3, 0, v3
	v_and_b32_e32 v4, 0xffff0000, v51
	v_mul_f32_e32 v5, v1, v1
	v_add_f32_e32 v3, v3, v14
	v_add_f32_e32 v4, 0, v4
	v_fmac_f32_e32 v5, v0, v0
	v_add_f32_e32 v4, v4, v15
	v_fmac_f32_e32 v5, v3, v3
	v_fmac_f32_e32 v5, v4, v4
	v_add_f32_e32 v79, v5, v2
	v_cvt_pk_bf16_f32 v0, v0, v1
	v_cvt_pk_bf16_f32 v1, v3, v4
	ds_write_b64 v241, v[0:1] offset:48
	s_waitcnt lgkmcnt(0)
; DI unsigned cvt_pk_bf16(float lo, float hi) { unsigned r; asm volatile("v_cvt_pk_bf16_f32 %0, %1, %2" : "=v"(r) : "v"(lo), "v"(hi)); return r; }
; DI float bf_lo(unsigned w) { return __uint_as_float(w << 16); }
; DI float bf_hi(unsigned w) { return __uint_as_float(w & 0xffff0000u); }
; #define MFMA32(a, b, c) __builtin_amdgcn_mfma_f32_32x32x16_bf16((a), (b), (c), 0, 0, 0)
; template <bool DRY, bool H1>
; DI void intra_phase(LAS unsigned char* lds, const Params& p) {
;     ...
;       for (int t = 0; t < 8; ++t) {
;         if (t < 7) {
; #pragma unroll
;           for (int s = 0; s < 8; ++s) va[(t + 1) & 1][s] = ldg16(vT, vo + (unsigned)(t + 1) * 8192u + 1024u * s);
; #pragma unroll
;           for (int gq = 0; gq < 4; ++gq) { yold[(t + 1) & 1][gq] = *(const u32x2*)((const char*)y + (yo + 64u * (t + 1) + 16u * gq)); if constexpr (H1) yol2[(t + 1) & 1][gq] = *(const u32x2*)((const char*)yb + (yo + 64u * (t + 1) + 16u * gq)); }
;         }
;         f32x16 yt;
; #pragma unroll
;         for (int i = 0; i < 16; ++i) yt[i] = 0.f;
; #pragma unroll
;         for (int s = 0; s < 8; ++s) yt = MFMA32(va[t & 1][s], pf[s], yt);
; #pragma unroll
;         for (int gq = 0; gq < 4; ++gq) {
;           const u32x2 ov = yold[t & 1][gq], o2 = yol2[t & 1][gq];
;           const float v0 = bf_lo(ov.x) + bf_lo(o2.x) + yt[4 * gq], v1 = bf_hi(ov.x) + bf_hi(o2.x) + yt[4 * gq + 1], v2 = bf_lo(ov.y) + bf_lo(o2.y) + yt[4 * gq + 2], v3 = bf_hi(ov.y) + bf_hi(o2.y) + yt[4 * gq + 3];
;           sq2 += v0 * v0 + v1 * v1 + v2 * v2 + v3 * v3;
;           u32x2 a; a.x = cvt_pk_bf16(v0, v1); a.y = cvt_pk_bf16(v2, v3); if (!DRY || v0 == 12345.678f) *(u32x2*)((char*)y + (yo + 64u * t + 16u * gq)) = a;
;         }
;         __builtin_amdgcn_sched_barrier(0);
;       }
	ds_read_b128 v[244:247], v242
	ds_read_b128 v[248:251], v242 offset:1152
	v_add_u32_e32 v253, 0x10000, v252
	s_waitcnt lgkmcnt(0)
	global_store_dwordx4 v252, v[244:247], s[82:83]
	global_store_dwordx4 v253, v[248:251], s[82:83]
	s_nop 1
	s_waitcnt vmcnt(11)
	v_mfma_f32_32x32x16_bf16 v[0:15], v[58:61], v[36:39], 0
	v_or_b32_e32 v50, 0xa000, v56
	v_or_b32_e32 v51, 0xa400, v56
	v_or_b32_e32 v54, 0xa800, v56
	v_or_b32_e32 v206, 0x140, v57
	v_or_b32_e32 v207, 0x150, v57
	v_or_b32_e32 v210, 0x160, v57
	v_or_b32_e32 v211, 0x170, v57
	s_waitcnt vmcnt(10)
	v_mfma_f32_32x32x16_bf16 v[0:15], v[62:65], v[32:35], v[0:15]
	global_load_dwordx4 v[58:61], v50, s[4:5]
	global_load_dwordx4 v[62:65], v51, s[4:5]
	v_or_b32_e32 v50, 0xac00, v56
	v_or_b32_e32 v51, 0xb400, v56
	s_waitcnt vmcnt(11)
	v_mfma_f32_32x32x16_bf16 v[0:15], v[66:69], v[44:47], v[0:15]
	global_load_dwordx4 v[66:69], v54, s[4:5]
	global_load_dwordx4 v[70:73], v50, s[4:5]
	v_or_b32_e32 v50, 0xb000, v56
	global_load_dwordx4 v[168:171], v50, s[4:5]
	global_load_dwordx4 v[172:175], v51, s[4:5]
	v_or_b32_e32 v50, 0xb800, v56
	v_or_b32_e32 v51, 0xbc00, v56
	s_waitcnt vmcnt(14)
	v_mfma_f32_32x32x16_bf16 v[0:15], v[80:83], v[40:43], v[0:15]
	global_load_dwordx4 v[80:83], v50, s[4:5]
	global_load_dwordx4 v[186:189], v51, s[4:5]
	v_add_u32_e32 v221, v206, v240
	global_load_dwordx4 v[232:235], v221, s[82:83]
	v_add_u32_e32 v222, 0x10000, v221
	global_load_dwordx4 v[236:239], v222, s[82:83]
	s_nop 0
	s_waitcnt vmcnt(17)
	v_mfma_f32_32x32x16_bf16 v[0:15], v[84:87], v[16:19], v[0:15]
	s_waitcnt vmcnt(12)
	s_waitcnt vmcnt(12)
	ds_write_b128 v242, v[224:227]
	ds_write_b128 v242, v[228:231] offset:1152
	s_waitcnt lgkmcnt(0)
	ds_read_b64 v[74:75], v241
	ds_read_b64 v[192:193], v241 offset:16
	ds_read_b64 v[52:53], v241 offset:32
	ds_read_b64 v[48:49], v241 offset:48
	s_waitcnt lgkmcnt(0)
	v_lshlrev_b32_e32 v84, 16, v74
	v_and_b32_e32 v74, 0xffff0000, v74
	v_add_f32_e32 v84, 0, v84
	v_add_f32_e32 v74, 0, v74
	v_lshlrev_b32_e32 v85, 16, v75
	v_and_b32_e32 v75, 0xffff0000, v75
	v_add_f32_e32 v85, 0, v85
	v_mfma_f32_32x32x16_bf16 v[0:15], v[178:181], v[20:23], v[0:15]
	s_waitcnt vmcnt(12)
	v_lshlrev_b32_e32 v86, 16, v192
	v_add_f32_e32 v75, 0, v75
	v_and_b32_e32 v87, 0xffff0000, v192
	v_add_f32_e32 v86, 0, v86
	v_add_f32_e32 v87, 0, v87
	v_mfma_f32_32x32x16_bf16 v[0:15], v[88:91], v[24:27], v[0:15]
	v_lshlrev_b32_e32 v88, 16, v193
	v_and_b32_e32 v89, 0xffff0000, v193
	v_add_f32_e32 v88, 0, v88
	v_add_f32_e32 v89, 0, v89
	v_mfma_f32_32x32x16_bf16 v[0:15], v[182:185], v[28:31], v[0:15]
	s_nop 11
	v_add_f32_e32 v84, v84, v0
	v_add_f32_e32 v0, v74, v1
	v_add_f32_e32 v2, v85, v2
	v_add_f32_e32 v3, v75, v3
	v_mul_f32_e32 v74, v0, v0
	v_cvt_pk_bf16_f32 v0, v84, v0
	v_cvt_pk_bf16_f32 v1, v2, v3
	v_add_f32_e32 v4, v86, v4
	v_add_f32_e32 v5, v87, v5
	v_add_f32_e32 v6, v88, v6
	v_add_f32_e32 v7, v89, v7
	v_add_u32_e32 v252, v167, v240
	ds_write_b64 v241, v[0:1]
	v_cvt_pk_bf16_f32 v0, v4, v5
	v_cvt_pk_bf16_f32 v1, v6, v7
	v_fmac_f32_e32 v74, v84, v84
	ds_write_b64 v241, v[0:1] offset:16
	s_waitcnt vmcnt(12)
	v_and_b32_e32 v1, 0xffff0000, v52
	v_mul_f32_e32 v75, v5, v5
	v_fmac_f32_e32 v74, v2, v2
	v_lshlrev_b32_e32 v0, 16, v52
	v_add_f32_e32 v1, 0, v1
	v_fmac_f32_e32 v75, v4, v4
	v_fmac_f32_e32 v74, v3, v3
	v_add_f32_e32 v0, 0, v0
	v_add_f32_e32 v1, v1, v9
	v_lshlrev_b32_e32 v3, 16, v53
	v_and_b32_e32 v4, 0xffff0000, v53
	v_add_f32_e32 v0, v0, v8
	v_add_f32_e32 v3, 0, v3
	v_add_f32_e32 v4, 0, v4
	v_mul_f32_e32 v5, v1, v1
	v_add_f32_e32 v3, v3, v10
	v_add_f32_e32 v4, v4, v11
	v_fmac_f32_e32 v5, v0, v0
	v_cvt_pk_bf16_f32 v0, v0, v1
	v_cvt_pk_bf16_f32 v1, v3, v4
	v_fmac_f32_e32 v75, v6, v6
	ds_write_b64 v241, v[0:1] offset:32
	s_waitcnt vmcnt(12)
	v_and_b32_e32 v1, 0xffff0000, v48
	v_fmac_f32_e32 v75, v7, v7
	v_add_f32_e32 v2, v79, v74
	v_fmac_f32_e32 v5, v3, v3
	v_lshlrev_b32_e32 v0, 16, v48
	v_add_f32_e32 v1, 0, v1
	v_add_f32_e32 v2, v75, v2
	v_fmac_f32_e32 v5, v4, v4
	v_add_f32_e32 v0, 0, v0
	v_add_f32_e32 v1, v1, v13
	v_lshlrev_b32_e32 v3, 16, v49
	v_add_f32_e32 v2, v5, v2
	v_add_f32_e32 v0, v0, v12
	v_add_f32_e32 v3, 0, v3
	v_and_b32_e32 v4, 0xffff0000, v49
	v_mul_f32_e32 v5, v1, v1
	v_add_f32_e32 v3, v3, v14
	v_add_f32_e32 v4, 0, v4
	v_fmac_f32_e32 v5, v0, v0
	v_add_f32_e32 v4, v4, v15
	v_fmac_f32_e32 v5, v3, v3
	v_fmac_f32_e32 v5, v4, v4
	v_add_f32_e32 v48, v5, v2
	v_cvt_pk_bf16_f32 v0, v0, v1
	v_cvt_pk_bf16_f32 v1, v3, v4
	ds_write_b64 v241, v[0:1] offset:48
	s_waitcnt lgkmcnt(0)
	ds_read_b128 v[244:247], v242
	ds_read_b128 v[248:251], v242 offset:1152
	v_add_u32_e32 v253, 0x10000, v252
	s_waitcnt lgkmcnt(0)
	global_store_dwordx4 v252, v[244:247], s[82:83]
	global_store_dwordx4 v253, v[248:251], s[82:83]
	s_nop 1
	s_waitcnt vmcnt(11)
	v_mfma_f32_32x32x16_bf16 v[0:15], v[58:61], v[36:39], 0
	v_or_b32_e32 v49, 0xc000, v56
	v_or_b32_e32 v52, 0xc400, v56
	v_or_b32_e32 v53, 0xc800, v56
	v_or_b32_e32 v176, 0x180, v57
	v_or_b32_e32 v203, 0x190, v57
	v_or_b32_e32 v215, 0x1a0, v57
	v_or_b32_e32 v216, 0x1b0, v57
	s_waitcnt vmcnt(10)
	v_mfma_f32_32x32x16_bf16 v[0:15], v[62:65], v[32:35], v[0:15]
	global_load_dwordx4 v[58:61], v49, s[4:5]
	global_load_dwordx4 v[62:65], v52, s[4:5]
	v_or_b32_e32 v49, 0xcc00, v56
	global_load_dwordx4 v[84:87], v53, s[4:5]
	global_load_dwordx4 v[178:181], v49, s[4:5]
	v_or_b32_e32 v49, 0xd000, v56
	v_or_b32_e32 v52, 0xd400, v56
	global_load_dwordx4 v[182:185], v49, s[4:5]
	global_load_dwordx4 v[190:193], v52, s[4:5]
	v_or_b32_e32 v49, 0xd800, v56
	s_waitcnt vmcnt(15)
	v_mfma_f32_32x32x16_bf16 v[0:15], v[66:69], v[44:47], v[0:15]
	v_or_b32_e32 v52, 0xdc00, v56
	s_waitcnt vmcnt(8)
	s_waitcnt vmcnt(8)
; DI unsigned cvt_pk_bf16(float lo, float hi) { unsigned r; asm volatile("v_cvt_pk_bf16_f32 %0, %1, %2" : "=v"(r) : "v"(lo), "v"(hi)); return r; }
; DI float bf_lo(unsigned w) { return __uint_as_float(w << 16); }
; DI float bf_hi(unsigned w) { return __uint_as_float(w & 0xffff0000u); }
; #define MFMA32(a, b, c) __builtin_amdgcn_mfma_f32_32x32x16_bf16((a), (b), (c), 0, 0, 0)
; template <bool DRY, bool H1>
; DI void intra_phase(LAS unsigned char* lds, const Params& p) {
;     ...
;       for (int t = 0; t < 8; ++t) {
;         if (t < 7) {
; #pragma unroll
;           for (int s = 0; s < 8; ++s) va[(t + 1) & 1][s] = ldg16(vT, vo + (unsigned)(t + 1) * 8192u + 1024u * s);
; #pragma unroll
;           for (int gq = 0; gq < 4; ++gq) { yold[(t + 1) & 1][gq] = *(const u32x2*)((const char*)y + (yo + 64u * (t + 1) + 16u * gq)); if constexpr (H1) yol2[(t + 1) & 1][gq] = *(const u32x2*)((const char*)yb + (yo + 64u * (t + 1) + 16u * gq)); }
;         }
;         f32x16 yt;
; #pragma unroll
;         for (int i = 0; i < 16; ++i) yt[i] = 0.f;
; #pragma unroll
;         for (int s = 0; s < 8; ++s) yt = MFMA32(va[t & 1][s], pf[s], yt);
; #pragma unroll
;         for (int gq = 0; gq < 4; ++gq) {
;           const u32x2 ov = yold[t & 1][gq], o2 = yol2[t & 1][gq];
;           const float v0 = bf_lo(ov.x) + bf_lo(o2.x) + yt[4 * gq], v1 = bf_hi(ov.x) + bf_hi(o2.x) + yt[4 * gq + 1], v2 = bf_lo(ov.y) + bf_lo(o2.y) + yt[4 * gq + 2], v3 = bf_hi(ov.y) + bf_hi(o2.y) + yt[4 * gq + 3];
;           sq2 += v0 * v0 + v1 * v1 + v2 * v2 + v3 * v3;
;           u32x2 a; a.x = cvt_pk_bf16(v0, v1); a.y = cvt_pk_bf16(v2, v3); if (!DRY || v0 == 12345.678f) *(u32x2*)((char*)y + (yo + 64u * t + 16u * gq)) = a;
;         }
;         __builtin_amdgcn_sched_barrier(0);
;       }
	ds_write_b128 v242, v[232:235]
	ds_write_b128 v242, v[236:239] offset:1152
	s_waitcnt lgkmcnt(0)
	ds_read_b64 v[198:199], v241
	ds_read_b64 v[200:201], v241 offset:16
	ds_read_b64 v[54:55], v241 offset:32
	ds_read_b64 v[50:51], v241 offset:48
	s_waitcnt lgkmcnt(0)
	v_lshlrev_b32_e32 v53, 16, v199
	v_and_b32_e32 v66, 0xffff0000, v199
	v_add_f32_e32 v53, 0, v53
	s_waitcnt vmcnt(8)
	v_lshlrev_b32_e32 v67, 16, v200
	v_add_f32_e32 v66, 0, v66
	v_and_b32_e32 v74, 0xffff0000, v201
	v_mfma_f32_32x32x16_bf16 v[0:15], v[70:73], v[40:43], v[0:15]
	global_load_dwordx4 v[194:197], v49, s[4:5]
	global_load_dwordx4 v[68:71], v52, s[4:5]
	v_add_u32_e32 v221, v176, v240
	global_load_dwordx4 v[224:227], v221, s[82:83]
	v_add_u32_e32 v222, 0x10000, v221
	global_load_dwordx4 v[228:231], v222, s[82:83]
	v_lshlrev_b32_e32 v49, 16, v198
	v_and_b32_e32 v52, 0xffff0000, v198
	v_add_f32_e32 v49, 0, v49
	v_add_f32_e32 v52, 0, v52
	v_and_b32_e32 v72, 0xffff0000, v200
	v_mfma_f32_32x32x16_bf16 v[0:15], v[168:171], v[16:19], v[0:15]
	v_lshlrev_b32_e32 v73, 16, v201
	v_add_f32_e32 v67, 0, v67
	v_add_f32_e32 v72, 0, v72
	v_add_f32_e32 v73, 0, v73
	v_add_f32_e32 v74, 0, v74
	v_mfma_f32_32x32x16_bf16 v[0:15], v[172:175], v[20:23], v[0:15]
	v_mfma_f32_32x32x16_bf16 v[0:15], v[80:83], v[24:27], v[0:15]
	v_mfma_f32_32x32x16_bf16 v[0:15], v[186:189], v[28:31], v[0:15]
	s_nop 11
	v_add_f32_e32 v49, v49, v0
	v_add_f32_e32 v0, v52, v1
	v_add_f32_e32 v2, v53, v2
	v_add_f32_e32 v3, v66, v3
	v_mul_f32_e32 v52, v0, v0
	v_cvt_pk_bf16_f32 v0, v49, v0
	v_cvt_pk_bf16_f32 v1, v2, v3
	v_add_f32_e32 v4, v67, v4
	v_add_f32_e32 v5, v72, v5
	v_add_f32_e32 v6, v73, v6
	v_add_f32_e32 v7, v74, v7
	v_add_u32_e32 v252, v206, v240
	ds_write_b64 v241, v[0:1]
	v_cvt_pk_bf16_f32 v0, v4, v5
	v_cvt_pk_bf16_f32 v1, v6, v7
	v_fmac_f32_e32 v52, v49, v49
	ds_write_b64 v241, v[0:1] offset:16
	s_waitcnt vmcnt(12)
	v_and_b32_e32 v1, 0xffff0000, v54
	v_mul_f32_e32 v53, v5, v5
	v_fmac_f32_e32 v52, v2, v2
	v_lshlrev_b32_e32 v0, 16, v54
	v_add_f32_e32 v1, 0, v1
	v_fmac_f32_e32 v53, v4, v4
	v_fmac_f32_e32 v52, v3, v3
	v_add_f32_e32 v0, 0, v0
	v_add_f32_e32 v1, v1, v9
	v_lshlrev_b32_e32 v3, 16, v55
	v_and_b32_e32 v4, 0xffff0000, v55
	v_add_f32_e32 v0, v0, v8
	v_add_f32_e32 v3, 0, v3
	v_add_f32_e32 v4, 0, v4
	v_mul_f32_e32 v5, v1, v1
	v_add_f32_e32 v3, v3, v10
	v_add_f32_e32 v4, v4, v11
	v_fmac_f32_e32 v5, v0, v0
	v_cvt_pk_bf16_f32 v0, v0, v1
	v_cvt_pk_bf16_f32 v1, v3, v4
	v_fmac_f32_e32 v53, v6, v6
	ds_write_b64 v241, v[0:1] offset:32
	s_waitcnt vmcnt(12)
	v_and_b32_e32 v1, 0xffff0000, v50
	v_fmac_f32_e32 v53, v7, v7
	v_add_f32_e32 v2, v48, v52
	v_fmac_f32_e32 v5, v3, v3
	v_lshlrev_b32_e32 v0, 16, v50
	v_add_f32_e32 v1, 0, v1
	v_add_f32_e32 v2, v53, v2
	v_fmac_f32_e32 v5, v4, v4
	v_add_f32_e32 v0, 0, v0
	v_add_f32_e32 v1, v1, v13
	v_lshlrev_b32_e32 v3, 16, v51
	v_add_f32_e32 v2, v5, v2
	v_add_f32_e32 v0, v0, v12
	v_add_f32_e32 v3, 0, v3
	v_and_b32_e32 v4, 0xffff0000, v51
	v_mul_f32_e32 v5, v1, v1
	v_add_f32_e32 v3, v3, v14
	v_add_f32_e32 v4, 0, v4
	v_fmac_f32_e32 v5, v0, v0
	v_add_f32_e32 v4, v4, v15
	v_fmac_f32_e32 v5, v3, v3
	v_fmac_f32_e32 v5, v4, v4
	v_add_f32_e32 v186, v5, v2
	v_cvt_pk_bf16_f32 v0, v0, v1
	v_cvt_pk_bf16_f32 v1, v3, v4
	ds_write_b64 v241, v[0:1] offset:48
	s_waitcnt lgkmcnt(0)
	ds_read_b128 v[244:247], v242
	ds_read_b128 v[248:251], v242 offset:1152
	v_add_u32_e32 v253, 0x10000, v252
	s_waitcnt lgkmcnt(0)
	global_store_dwordx4 v252, v[244:247], s[82:83]
	global_store_dwordx4 v253, v[248:251], s[82:83]
	s_nop 1
	s_waitcnt vmcnt(11)
	v_mfma_f32_32x32x16_bf16 v[0:15], v[58:61], v[36:39], 0
	v_or_b32_e32 v48, 0xe000, v56
	v_or_b32_e32 v49, 0xe400, v56
	v_or_b32_e32 v50, 0xe800, v56
	v_or_b32_e32 v51, 0xec00, v56
	global_load_dwordx4 v[168:171], v48, s[4:5]
	global_load_dwordx4 v[172:175], v49, s[4:5]
	v_or_b32_e32 v48, 0xf000, v56
	v_or_b32_e32 v52, 0xf400, v56
	s_waitcnt vmcnt(12)
	v_mfma_f32_32x32x16_bf16 v[0:15], v[62:65], v[32:35], v[0:15]
	v_or_b32_e32 v58, 0xf800, v56
	v_or_b32_e32 v60, 0xfc00, v56
	global_load_dwordx4 v[72:75], v50, s[4:5]
	global_load_dwordx4 v[64:67], v51, s[4:5]
	s_nop 0
	global_load_dwordx4 v[48:51], v48, s[4:5]
	s_nop 0
	global_load_dwordx4 v[52:55], v52, s[4:5]
	v_or_b32_e32 v167, 0x1e0, v57
	v_or_b32_e32 v79, 0x1f0, v57
	s_waitcnt vmcnt(8)
	s_waitcnt vmcnt(8)
	ds_write_b128 v242, v[224:227]
	ds_write_b128 v242, v[228:231] offset:1152
	s_waitcnt lgkmcnt(0)
	ds_read_b64 v[204:205], v241
	ds_read_b64 v[208:209], v241 offset:16
	ds_read_b64 v[90:91], v241 offset:32
	ds_read_b64 v[88:89], v241 offset:48
	s_waitcnt lgkmcnt(0)
	v_lshlrev_b32_e32 v187, 16, v209
	v_mfma_f32_32x32x16_bf16 v[0:15], v[84:87], v[44:47], v[0:15]
	v_and_b32_e32 v188, 0xffff0000, v209
	v_add_f32_e32 v187, 0, v187
	v_add_f32_e32 v188, 0, v188
	s_waitcnt vmcnt(8)
; DI unsigned cvt_pk_bf16(float lo, float hi) { unsigned r; asm volatile("v_cvt_pk_bf16_f32 %0, %1, %2" : "=v"(r) : "v"(lo), "v"(hi)); return r; }
; DI float bf_lo(unsigned w) { return __uint_as_float(w << 16); }
; DI float bf_hi(unsigned w) { return __uint_as_float(w & 0xffff0000u); }
; DI float shx(float v, int lane, int mask) { return __int_as_float(__builtin_amdgcn_ds_bpermute((lane ^ mask) << 2, __float_as_int(v))); }
; #define MFMA32(a, b, c) __builtin_amdgcn_mfma_f32_32x32x16_bf16((a), (b), (c), 0, 0, 0)
; template <bool DRY, bool H1>
; DI void intra_phase(LAS unsigned char* lds, const Params& p) {
;     ...
;       for (int t = 0; t < 8; ++t) {
;         if (t < 7) {
; #pragma unroll
;           for (int s = 0; s < 8; ++s) va[(t + 1) & 1][s] = ldg16(vT, vo + (unsigned)(t + 1) * 8192u + 1024u * s);
; #pragma unroll
;           for (int gq = 0; gq < 4; ++gq) { yold[(t + 1) & 1][gq] = *(const u32x2*)((const char*)y + (yo + 64u * (t + 1) + 16u * gq)); if constexpr (H1) yol2[(t + 1) & 1][gq] = *(const u32x2*)((const char*)yb + (yo + 64u * (t + 1) + 16u * gq)); }
;         }
;         f32x16 yt;
; #pragma unroll
;         for (int i = 0; i < 16; ++i) yt[i] = 0.f;
; #pragma unroll
;         for (int s = 0; s < 8; ++s) yt = MFMA32(va[t & 1][s], pf[s], yt);
; #pragma unroll
;         for (int gq = 0; gq < 4; ++gq) {
;           const u32x2 ov = yold[t & 1][gq], o2 = yol2[t & 1][gq];
;           const float v0 = bf_lo(ov.x) + bf_lo(o2.x) + yt[4 * gq], v1 = bf_hi(ov.x) + bf_hi(o2.x) + yt[4 * gq + 1], v2 = bf_lo(ov.y) + bf_lo(o2.y) + yt[4 * gq + 2], v3 = bf_hi(ov.y) + bf_hi(o2.y) + yt[4 * gq + 3];
;           sq2 += v0 * v0 + v1 * v1 + v2 * v2 + v3 * v3;
;           u32x2 a; a.x = cvt_pk_bf16(v0, v1); a.y = cvt_pk_bf16(v2, v3); if (!DRY || v0 == 12345.678f) *(u32x2*)((char*)y + (yo + 64u * t + 16u * gq)) = a;
;         }
;         __builtin_amdgcn_sched_barrier(0);
;       }
;       sq2 += shx(sq2, lane, 32);
;       if (h == 0 && (!DRY || sq2 == 12345.678f)) ss[((size_t)(tb + icol) * 4 + hd) * 16 + wh] = sq2;
	v_lshlrev_b32_e32 v189, 16, v90
	v_and_b32_e32 v90, 0xffff0000, v90
	v_add_f32_e32 v189, 0, v189
	v_add_f32_e32 v90, 0, v90
	v_mfma_f32_32x32x16_bf16 v[0:15], v[178:181], v[40:43], v[0:15]
	v_or_b32_e32 v178, 0x1c0, v57
	v_or_b32_e32 v179, 0x1d0, v57
	global_load_dwordx4 v[56:59], v58, s[4:5]
	s_nop 0
	global_load_dwordx4 v[60:63], v60, s[4:5]
	s_nop 0
	v_add_u32_e32 v221, v178, v240
	global_load_dwordx4 v[232:235], v221, s[82:83]
	v_add_u32_e32 v222, 0x10000, v221
	global_load_dwordx4 v[236:239], v222, s[82:83]
	v_lshlrev_b32_e32 v180, 16, v204
	v_and_b32_e32 v181, 0xffff0000, v204
	v_add_f32_e32 v180, 0, v180
	v_mfma_f32_32x32x16_bf16 v[0:15], v[182:185], v[16:19], v[0:15]
	v_add_f32_e32 v181, 0, v181
	v_lshlrev_b32_e32 v182, 16, v205
	v_and_b32_e32 v183, 0xffff0000, v205
	v_lshlrev_b32_e32 v184, 16, v208
	v_and_b32_e32 v185, 0xffff0000, v208
	v_add_f32_e32 v182, 0, v182
	v_add_f32_e32 v183, 0, v183
	v_mfma_f32_32x32x16_bf16 v[0:15], v[190:193], v[20:23], v[0:15]
	v_add_f32_e32 v184, 0, v184
	v_add_f32_e32 v185, 0, v185
	v_mfma_f32_32x32x16_bf16 v[0:15], v[194:197], v[24:27], v[0:15]
	v_mfma_f32_32x32x16_bf16 v[0:15], v[68:71], v[28:31], v[0:15]
	s_nop 11
	v_add_f32_e32 v68, v180, v0
	v_add_f32_e32 v69, v181, v1
	v_cvt_pk_bf16_f32 v0, v68, v69
	v_add_f32_e32 v2, v182, v2
	v_add_f32_e32 v3, v183, v3
	v_add_f32_e32 v4, v184, v4
	v_add_f32_e32 v5, v185, v5
	v_cvt_pk_bf16_f32 v1, v2, v3
	v_add_u32_e32 v252, v176, v240
	ds_write_b64 v241, v[0:1]
	v_cvt_pk_bf16_f32 v0, v4, v5
	v_add_f32_e32 v6, v187, v6
	v_add_f32_e32 v7, v188, v7
	v_cvt_pk_bf16_f32 v1, v6, v7
	ds_write_b64 v241, v[0:1] offset:16
	v_lshlrev_b32_e32 v0, 16, v91
	v_add_f32_e32 v0, 0, v0
	v_add_f32_e32 v10, v0, v10
	v_and_b32_e32 v0, 0xffff0000, v91
	v_add_f32_e32 v0, 0, v0
	v_add_f32_e32 v8, v189, v8
	v_add_f32_e32 v9, v90, v9
	v_add_f32_e32 v11, v0, v11
	v_cvt_pk_bf16_f32 v0, v8, v9
	v_cvt_pk_bf16_f32 v1, v10, v11
	ds_write_b64 v241, v[0:1] offset:32
	s_waitcnt vmcnt(12)
	v_lshlrev_b32_e32 v0, 16, v88
	v_add_f32_e32 v0, 0, v0
	v_add_f32_e32 v12, v0, v12
	v_and_b32_e32 v0, 0xffff0000, v88
	v_add_f32_e32 v0, 0, v0
	v_add_f32_e32 v13, v0, v13
	v_lshlrev_b32_e32 v0, 16, v89
	v_add_f32_e32 v0, 0, v0
	v_add_f32_e32 v14, v0, v14
	v_and_b32_e32 v0, 0xffff0000, v89
	v_add_f32_e32 v0, 0, v0
	v_add_f32_e32 v15, v0, v15
	v_cvt_pk_bf16_f32 v0, v12, v13
	v_cvt_pk_bf16_f32 v1, v14, v15
	ds_write_b64 v241, v[0:1] offset:48
	s_waitcnt lgkmcnt(0)
	ds_read_b128 v[244:247], v242
	ds_read_b128 v[248:251], v242 offset:1152
	v_add_u32_e32 v253, 0x10000, v252
	s_waitcnt lgkmcnt(0)
	global_store_dwordx4 v252, v[244:247], s[82:83]
	global_store_dwordx4 v253, v[248:251], s[82:83]
	s_nop 1
	v_mul_f32_e32 v0, v69, v69
	v_fmac_f32_e32 v0, v68, v68
	v_mul_f32_e32 v1, v5, v5
	v_fmac_f32_e32 v0, v2, v2
	v_fmac_f32_e32 v1, v4, v4
	v_fmac_f32_e32 v0, v3, v3
	v_fmac_f32_e32 v1, v6, v6
	v_add_f32_e32 v0, v186, v0
	v_fmac_f32_e32 v1, v7, v7
	v_add_f32_e32 v0, v1, v0
	v_mul_f32_e32 v1, v9, v9
	v_fmac_f32_e32 v1, v8, v8
	v_fmac_f32_e32 v1, v10, v10
	v_fmac_f32_e32 v1, v11, v11
	v_add_f32_e32 v0, v1, v0
	v_mul_f32_e32 v1, v13, v13
	v_fmac_f32_e32 v1, v12, v12
	v_fmac_f32_e32 v1, v14, v14
	v_fmac_f32_e32 v1, v15, v15
	v_add_f32_e32 v68, v1, v0
	s_waitcnt vmcnt(11)
	v_mfma_f32_32x32x16_bf16 v[0:15], v[168:171], v[36:39], 0
	s_waitcnt vmcnt(10)
	v_mfma_f32_32x32x16_bf16 v[0:15], v[172:175], v[32:35], v[0:15]
	s_waitcnt vmcnt(9)
	v_mfma_f32_32x32x16_bf16 v[0:15], v[72:75], v[44:47], v[0:15]
	s_waitcnt vmcnt(8)
	v_mfma_f32_32x32x16_bf16 v[0:15], v[64:67], v[40:43], v[0:15]
	s_waitcnt vmcnt(7)
	v_mfma_f32_32x32x16_bf16 v[0:15], v[48:51], v[16:19], v[0:15]
	s_waitcnt vmcnt(2)
	s_waitcnt vmcnt(2)
	ds_write_b128 v242, v[232:235]
	ds_write_b128 v242, v[236:239] offset:1152
	s_waitcnt lgkmcnt(0)
	ds_read_b64 v[86:87], v241
	ds_read_b64 v[84:85], v241 offset:16
	ds_read_b64 v[82:83], v241 offset:32
	ds_read_b64 v[80:81], v241 offset:48
	s_waitcnt lgkmcnt(0)
	v_lshlrev_b32_e32 v16, 16, v86
	v_add_f32_e32 v16, 0, v16
	v_mfma_f32_32x32x16_bf16 v[0:15], v[52:55], v[20:23], v[0:15]
	v_mfma_f32_32x32x16_bf16 v[0:15], v[56:59], v[24:27], v[0:15]
	v_mfma_f32_32x32x16_bf16 v[0:15], v[60:63], v[28:31], v[0:15]
	s_nop 11
	v_add_f32_e32 v0, v16, v0
	v_and_b32_e32 v16, 0xffff0000, v86
	v_add_f32_e32 v16, 0, v16
	v_add_f32_e32 v1, v16, v1
	v_lshlrev_b32_e32 v16, 16, v87
	v_add_f32_e32 v16, 0, v16
	v_add_f32_e32 v2, v16, v2
	v_and_b32_e32 v16, 0xffff0000, v87
	v_add_f32_e32 v16, 0, v16
	v_add_f32_e32 v3, v16, v3
	v_mul_f32_e32 v16, v1, v1
	v_fmac_f32_e32 v16, v0, v0
	v_cvt_pk_bf16_f32 v0, v0, v1
	v_cvt_pk_bf16_f32 v1, v2, v3
	v_add_u32_e32 v252, v178, v240
	ds_write_b64 v241, v[0:1]
	s_waitcnt vmcnt(2)
	v_and_b32_e32 v1, 0xffff0000, v84
	v_fmac_f32_e32 v16, v2, v2
	v_lshlrev_b32_e32 v0, 16, v84
	v_add_f32_e32 v1, 0, v1
	v_fmac_f32_e32 v16, v3, v3
	v_add_f32_e32 v0, 0, v0
	v_add_f32_e32 v1, v1, v5
	v_lshlrev_b32_e32 v2, 16, v85
	v_and_b32_e32 v3, 0xffff0000, v85
	v_add_f32_e32 v0, v0, v4
	v_add_f32_e32 v2, 0, v2
	v_add_f32_e32 v3, 0, v3
	v_mul_f32_e32 v4, v1, v1
	v_add_f32_e32 v2, v2, v6
	v_add_f32_e32 v3, v3, v7
	v_fmac_f32_e32 v4, v0, v0
	v_cvt_pk_bf16_f32 v0, v0, v1
	v_cvt_pk_bf16_f32 v1, v2, v3
	ds_write_b64 v241, v[0:1] offset:16
	s_waitcnt vmcnt(2)
	v_and_b32_e32 v1, 0xffff0000, v82
	v_lshlrev_b32_e32 v0, 16, v82
	v_add_f32_e32 v1, 0, v1
	v_fmac_f32_e32 v4, v2, v2
	v_add_f32_e32 v0, 0, v0
	v_add_f32_e32 v1, v1, v9
	v_fmac_f32_e32 v4, v3, v3
	v_add_f32_e32 v0, v0, v8
	v_lshlrev_b32_e32 v2, 16, v83
	v_and_b32_e32 v3, 0xffff0000, v83
	v_mul_f32_e32 v5, v1, v1
	v_add_f32_e32 v2, 0, v2
	v_add_f32_e32 v3, 0, v3
	v_fmac_f32_e32 v5, v0, v0
	v_cvt_pk_bf16_f32 v0, v0, v1
	v_add_f32_e32 v2, v2, v10
	v_add_f32_e32 v3, v3, v11
	v_cvt_pk_bf16_f32 v1, v2, v3
	ds_write_b64 v241, v[0:1] offset:32
	s_waitcnt vmcnt(2)
	v_lshlrev_b32_e32 v0, 16, v80
	v_add_f32_e32 v0, 0, v0
	v_add_f32_e32 v1, v0, v12
	v_and_b32_e32 v0, 0xffff0000, v80
	v_add_f32_e32 v0, 0, v0
	v_fmac_f32_e32 v5, v2, v2
	v_add_f32_e32 v2, v0, v13
	v_lshlrev_b32_e32 v0, 16, v81
	v_add_f32_e32 v0, 0, v0
	v_add_f32_e32 v16, v68, v16
	v_fmac_f32_e32 v5, v3, v3
	v_add_f32_e32 v3, v0, v14
	v_and_b32_e32 v0, 0xffff0000, v81
	v_add_f32_e32 v4, v4, v16
	v_add_f32_e32 v0, 0, v0
	v_add_f32_e32 v4, v5, v4
	v_add_f32_e32 v5, v0, v15
	v_mul_f32_e32 v0, v2, v2
	v_fmac_f32_e32 v0, v1, v1
	v_fmac_f32_e32 v0, v3, v3
	v_fmac_f32_e32 v0, v5, v5
	v_add_f32_e32 v0, v0, v4
	v_cvt_pk_bf16_f32 v2, v1, v2
	v_cvt_pk_bf16_f32 v3, v3, v5
	ds_write_b64 v241, v[2:3] offset:48
	s_waitcnt lgkmcnt(0)
	ds_read_b128 v[244:247], v242
	ds_read_b128 v[248:251], v242 offset:1152
	v_add_u32_e32 v253, 0x10000, v252
	s_waitcnt lgkmcnt(0)
	global_store_dwordx4 v252, v[244:247], s[82:83]
	global_store_dwordx4 v253, v[248:251], s[82:83]
	s_nop 1
	ds_bpermute_b32 v1, v96, v0
	v_readlane_b32 s60, v255, 47
	v_readlane_b32 s61, v255, 48
	s_and_saveexec_b64 s[96:97], s[60:61]
	s_cbranch_execz .LBB0_57
; DI float shx(float v, int lane, int mask) { return __int_as_float(__builtin_amdgcn_ds_bpermute((lane ^ mask) << 2, __float_as_int(v))); }
; template <bool DRY, bool H1>
; DI void intra_phase(LAS unsigned char* lds, const Params& p) {
;     ...
;       sq2 += shx(sq2, lane, 32);
;       if (h == 0 && (!DRY || sq2 == 12345.678f)) ss[((size_t)(tb + icol) * 4 + hd) * 16 + wh] = sq2;
	v_ashrrev_i32_e32 v79, 31, v78
	v_readlane_b32 s60, v255, 45
	s_waitcnt lgkmcnt(0)
	v_add_f32_e32 v2, v0, v1
	v_lshlrev_b64 v[0:1], 8, v[78:79]
	v_readlane_b32 s61, v255, 46
	s_lshl_b32 s94, s94, 6
	s_nop 0
	v_lshl_add_u64 v[0:1], s[60:61], 0, v[0:1]
	v_lshl_add_u64 v[0:1], v[0:1], 0, s[94:95]
	v_lshl_add_u64 v[0:1], v[76:77], 2, v[0:1]
	global_store_dword v[0:1], v2, off
	s_branch .LBB0_57
